# residual GEMM epilogue: 32 serialized load-wait-add-store round trips replaced by two batches of 16 loads in flight (global_load/store, same adds)
# speedup vs baseline: 1.1159x; 1.0123x over previous
;     __device__ __forceinline__ void operator()(const f32x4 (&acc)[2][2][4][2], const Unit& u, int wr, int wc, int fr, int fq) const {
;         const int col0 = u.pn * BM + wc * 32 + 4 * fq;
; #pragma unroll
;         for (int ai = 0; ai < 2; ++ai)
; #pragma unroll
;             for (int m = 0; m < 4; ++m) { float* rp = H + (size_t)(u.pm * BM + ai * HALF + wr * 64 + m * 16 + fr) * ldc + col0;
; #pragma unroll
;                 for (int bj = 0; bj < 2; ++bj)
; #pragma unroll
;                     for (int n = 0; n < 2; ++n) { f32x4* p = (f32x4*)(rp + bj * HALF + n * 16); f32x4 h = *p; h += acc[ai][bj][m][n] * scale; *p = h; } }
.LBB0_172:
	v_lshl_add_u32 v146, s3, 8, v131
	v_lshl_or_b32 v144, s2, 8, v134
	v_ashrrev_i32_e32 v145, 31, v144
	s_mov_b64 s[82:83], -1
	v_lshlrev_b64 v[144:145], 2, v[144:145]
	s_and_b64 vcc, exec, s[4:5]
	v_mov_b32_e32 v162, v146
	v_ashrrev_i32_e32 v163, 31, v162
	v_lshlrev_b64 v[162:163], 12, v[162:163]
	v_lshl_add_u64 v[162:163], s[22:23], 0, v[162:163]
	v_lshl_add_u64 v[162:163], v[162:163], 0, v[144:145]
	v_add_u32_e32 v164, 0x10, v146
	v_ashrrev_i32_e32 v165, 31, v164
	v_lshlrev_b64 v[164:165], 12, v[164:165]
	v_lshl_add_u64 v[164:165], s[22:23], 0, v[164:165]
	v_lshl_add_u64 v[164:165], v[164:165], 0, v[144:145]
	v_add_u32_e32 v180, 0x20, v146
	v_ashrrev_i32_e32 v181, 31, v180
	v_lshlrev_b64 v[180:181], 12, v[180:181]
	v_lshl_add_u64 v[180:181], s[22:23], 0, v[180:181]
	v_lshl_add_u64 v[180:181], v[180:181], 0, v[144:145]
	v_add_u32_e32 v250, 0x30, v146
	v_ashrrev_i32_e32 v251, 31, v250
	v_lshlrev_b64 v[250:251], 12, v[250:251]
	v_lshl_add_u64 v[250:251], s[22:23], 0, v[250:251]
	v_lshl_add_u64 v[250:251], v[250:251], 0, v[144:145]
	global_load_dwordx4 v[194:197], v[162:163], off
	global_load_dwordx4 v[198:201], v[162:163], off offset:64
	global_load_dwordx4 v[202:205], v[162:163], off offset:512
	global_load_dwordx4 v[210:213], v[162:163], off offset:576
	global_load_dwordx4 v[214:217], v[164:165], off
	global_load_dwordx4 v[218:221], v[164:165], off offset:64
	global_load_dwordx4 v[222:225], v[164:165], off offset:512
	global_load_dwordx4 v[226:229], v[164:165], off offset:576
	global_load_dwordx4 v[230:233], v[180:181], off
	global_load_dwordx4 v[234:237], v[180:181], off offset:64
	global_load_dwordx4 v[238:241], v[180:181], off offset:512
	global_load_dwordx4 v[242:245], v[180:181], off offset:576
	global_load_dwordx4 v[150:153], v[250:251], off
	global_load_dwordx4 v[154:157], v[250:251], off offset:64
	global_load_dwordx4 v[158:161], v[250:251], off offset:512
	global_load_dwordx4 v[246:249], v[250:251], off offset:576
	s_waitcnt vmcnt(15)
	v_pk_add_f32 v[126:127], v[126:127], v[196:197]
	v_pk_add_f32 v[124:125], v[124:125], v[194:195]
	global_store_dwordx4 v[162:163], v[124:127], off
	s_waitcnt vmcnt(15)
	v_pk_add_f32 v[122:123], v[122:123], v[200:201]
	v_pk_add_f32 v[120:121], v[120:121], v[198:199]
	global_store_dwordx4 v[162:163], v[120:123], off offset:64
	s_waitcnt vmcnt(15)
	v_pk_add_f32 v[118:119], v[118:119], v[204:205]
	v_pk_add_f32 v[116:117], v[116:117], v[202:203]
	global_store_dwordx4 v[162:163], v[116:119], off offset:512
	s_waitcnt vmcnt(15)
	v_pk_add_f32 v[114:115], v[114:115], v[212:213]
	v_pk_add_f32 v[112:113], v[112:113], v[210:211]
	global_store_dwordx4 v[162:163], v[112:115], off offset:576
	s_waitcnt vmcnt(15)
	v_pk_add_f32 v[110:111], v[110:111], v[216:217]
	v_pk_add_f32 v[108:109], v[108:109], v[214:215]
	global_store_dwordx4 v[164:165], v[108:111], off
	s_waitcnt vmcnt(15)
	v_pk_add_f32 v[106:107], v[106:107], v[220:221]
	v_pk_add_f32 v[104:105], v[104:105], v[218:219]
	global_store_dwordx4 v[164:165], v[104:107], off offset:64
	s_waitcnt vmcnt(15)
	v_pk_add_f32 v[102:103], v[102:103], v[224:225]
	v_pk_add_f32 v[100:101], v[100:101], v[222:223]
	global_store_dwordx4 v[164:165], v[100:103], off offset:512
	s_waitcnt vmcnt(15)
	v_pk_add_f32 v[98:99], v[98:99], v[228:229]
	v_pk_add_f32 v[96:97], v[96:97], v[226:227]
	global_store_dwordx4 v[164:165], v[96:99], off offset:576
	s_waitcnt vmcnt(15)
	v_pk_add_f32 v[94:95], v[94:95], v[232:233]
	v_pk_add_f32 v[92:93], v[92:93], v[230:231]
	global_store_dwordx4 v[180:181], v[92:95], off
	s_waitcnt vmcnt(15)
	v_pk_add_f32 v[90:91], v[90:91], v[236:237]
	v_pk_add_f32 v[88:89], v[88:89], v[234:235]
	global_store_dwordx4 v[180:181], v[88:91], off offset:64
	s_waitcnt vmcnt(15)
	v_pk_add_f32 v[86:87], v[86:87], v[240:241]
	v_pk_add_f32 v[84:85], v[84:85], v[238:239]
	global_store_dwordx4 v[180:181], v[84:87], off offset:512
	s_waitcnt vmcnt(15)
	v_pk_add_f32 v[82:83], v[82:83], v[244:245]
	v_pk_add_f32 v[80:81], v[80:81], v[242:243]
	global_store_dwordx4 v[180:181], v[80:83], off offset:576
	s_waitcnt vmcnt(15)
	v_pk_add_f32 v[78:79], v[78:79], v[152:153]
	v_pk_add_f32 v[76:77], v[76:77], v[150:151]
	global_store_dwordx4 v[250:251], v[76:79], off
	s_waitcnt vmcnt(15)
	v_pk_add_f32 v[74:75], v[74:75], v[156:157]
	v_pk_add_f32 v[72:73], v[72:73], v[154:155]
	global_store_dwordx4 v[250:251], v[72:75], off offset:64
	s_waitcnt vmcnt(15)
	v_pk_add_f32 v[70:71], v[70:71], v[160:161]
	v_pk_add_f32 v[68:69], v[68:69], v[158:159]
	global_store_dwordx4 v[250:251], v[68:71], off offset:512
	s_waitcnt vmcnt(15)
; #define PG8_BAR __builtin_amdgcn_s_barrier()
;     __device__ __forceinline__ void operator()(const f32x4 (&acc)[2][2][4][2], const Unit& u, int wr, int wc, int fr, int fq) const {
;     ...
;         for (int ai = 0; ai < 2; ++ai)
; #pragma unroll
;             for (int m = 0; m < 4; ++m) { float* rp = H + (size_t)(u.pm * BM + ai * HALF + wr * 64 + m * 16 + fr) * ldc + col0;
; #pragma unroll
;                 for (int bj = 0; bj < 2; ++bj)
; #pragma unroll
;                     for (int n = 0; n < 2; ++n) { f32x4* p = (f32x4*)(rp + bj * HALF + n * 16); f32x4 h = *p; h += acc[ai][bj][m][n] * scale; *p = h; } }
; template <class Epi, class Sched, bool ALIGN_EPI = false, bool SP2 = false>
; __device__ __forceinline__ void gemm_phase(PG8_LAS unsigned char* lds, const Gemm g, const Sched& S, const Epi& E) {
;     ...
;         if constexpr (ALIGN_EPI) { if (wr == 0) PG8_BAR; }
;         if constexpr (!Epi::AFTER_DRAIN) { E(acc, cur, wr, wc, fr, fq); S.done(cur); }
;         if (!has_next) break;
; #pragma unroll
;         for (int a = 0; a < 2; ++a)
; #pragma unroll
;             for (int b = 0; b < 2; ++b)
; #pragma unroll
;                 for (int m = 0; m < 4; ++m)
; #pragma unroll
;                     for (int n = 0; n < 2; ++n) acc[a][b][m][n] = (f32x4){0.f, 0.f, 0.f, 0.f};
;         cur = nxt; cA = nA; cB = nB; ++ui;
;         if constexpr (ALIGN_EPI) { if (wr == 1) PG8_BAR; }
	v_pk_add_f32 v[66:67], v[66:67], v[248:249]
	v_pk_add_f32 v[64:65], v[64:65], v[246:247]
	global_store_dwordx4 v[250:251], v[64:67], off offset:576
	v_add_u32_e32 v162, 0x80, v146
	v_ashrrev_i32_e32 v163, 31, v162
	v_lshlrev_b64 v[162:163], 12, v[162:163]
	v_lshl_add_u64 v[162:163], s[22:23], 0, v[162:163]
	v_lshl_add_u64 v[162:163], v[162:163], 0, v[144:145]
	v_add_u32_e32 v164, 0x90, v146
	v_ashrrev_i32_e32 v165, 31, v164
	v_lshlrev_b64 v[164:165], 12, v[164:165]
	v_lshl_add_u64 v[164:165], s[22:23], 0, v[164:165]
	v_lshl_add_u64 v[164:165], v[164:165], 0, v[144:145]
	v_add_u32_e32 v180, 0xa0, v146
	v_ashrrev_i32_e32 v181, 31, v180
	v_lshlrev_b64 v[180:181], 12, v[180:181]
	v_lshl_add_u64 v[180:181], s[22:23], 0, v[180:181]
	v_lshl_add_u64 v[180:181], v[180:181], 0, v[144:145]
	v_add_u32_e32 v250, 0xb0, v146
	v_ashrrev_i32_e32 v251, 31, v250
	v_lshlrev_b64 v[250:251], 12, v[250:251]
	v_lshl_add_u64 v[250:251], s[22:23], 0, v[250:251]
	v_lshl_add_u64 v[250:251], v[250:251], 0, v[144:145]
	global_load_dwordx4 v[194:197], v[162:163], off
	global_load_dwordx4 v[198:201], v[162:163], off offset:64
	global_load_dwordx4 v[202:205], v[162:163], off offset:512
	global_load_dwordx4 v[210:213], v[162:163], off offset:576
	global_load_dwordx4 v[214:217], v[164:165], off
	global_load_dwordx4 v[218:221], v[164:165], off offset:64
	global_load_dwordx4 v[222:225], v[164:165], off offset:512
	global_load_dwordx4 v[226:229], v[164:165], off offset:576
	global_load_dwordx4 v[230:233], v[180:181], off
	global_load_dwordx4 v[234:237], v[180:181], off offset:64
	global_load_dwordx4 v[238:241], v[180:181], off offset:512
	global_load_dwordx4 v[242:245], v[180:181], off offset:576
	global_load_dwordx4 v[150:153], v[250:251], off
	global_load_dwordx4 v[154:157], v[250:251], off offset:64
	global_load_dwordx4 v[158:161], v[250:251], off offset:512
	global_load_dwordx4 v[246:249], v[250:251], off offset:576
	s_waitcnt vmcnt(15)
	v_pk_add_f32 v[62:63], v[62:63], v[196:197]
	v_pk_add_f32 v[60:61], v[60:61], v[194:195]
	global_store_dwordx4 v[162:163], v[60:63], off
	s_waitcnt vmcnt(15)
	v_pk_add_f32 v[58:59], v[58:59], v[200:201]
	v_pk_add_f32 v[56:57], v[56:57], v[198:199]
	global_store_dwordx4 v[162:163], v[56:59], off offset:64
	s_waitcnt vmcnt(15)
	v_pk_add_f32 v[54:55], v[54:55], v[204:205]
	v_pk_add_f32 v[52:53], v[52:53], v[202:203]
	global_store_dwordx4 v[162:163], v[52:55], off offset:512
	s_waitcnt vmcnt(15)
	v_pk_add_f32 v[50:51], v[50:51], v[212:213]
	v_pk_add_f32 v[48:49], v[48:49], v[210:211]
	global_store_dwordx4 v[162:163], v[48:51], off offset:576
	s_waitcnt vmcnt(15)
	v_pk_add_f32 v[46:47], v[46:47], v[216:217]
	v_pk_add_f32 v[44:45], v[44:45], v[214:215]
	global_store_dwordx4 v[164:165], v[44:47], off
	s_waitcnt vmcnt(15)
	v_pk_add_f32 v[42:43], v[42:43], v[220:221]
	v_pk_add_f32 v[40:41], v[40:41], v[218:219]
	global_store_dwordx4 v[164:165], v[40:43], off offset:64
	s_waitcnt vmcnt(15)
	v_pk_add_f32 v[38:39], v[38:39], v[224:225]
	v_pk_add_f32 v[36:37], v[36:37], v[222:223]
	global_store_dwordx4 v[164:165], v[36:39], off offset:512
	s_waitcnt vmcnt(15)
	v_pk_add_f32 v[34:35], v[34:35], v[228:229]
	v_pk_add_f32 v[32:33], v[32:33], v[226:227]
	global_store_dwordx4 v[164:165], v[32:35], off offset:576
	s_waitcnt vmcnt(15)
	v_pk_add_f32 v[30:31], v[30:31], v[232:233]
	v_pk_add_f32 v[28:29], v[28:29], v[230:231]
	global_store_dwordx4 v[180:181], v[28:31], off
	s_waitcnt vmcnt(15)
	v_pk_add_f32 v[26:27], v[26:27], v[236:237]
	v_pk_add_f32 v[24:25], v[24:25], v[234:235]
	global_store_dwordx4 v[180:181], v[24:27], off offset:64
	s_waitcnt vmcnt(15)
	v_pk_add_f32 v[22:23], v[22:23], v[240:241]
	v_pk_add_f32 v[20:21], v[20:21], v[238:239]
	global_store_dwordx4 v[180:181], v[20:23], off offset:512
	s_waitcnt vmcnt(15)
	v_pk_add_f32 v[18:19], v[18:19], v[244:245]
	v_pk_add_f32 v[16:17], v[16:17], v[242:243]
	global_store_dwordx4 v[180:181], v[16:19], off offset:576
	s_waitcnt vmcnt(15)
	v_pk_add_f32 v[14:15], v[14:15], v[152:153]
	v_pk_add_f32 v[12:13], v[12:13], v[150:151]
	global_store_dwordx4 v[250:251], v[12:15], off
	s_waitcnt vmcnt(15)
	v_pk_add_f32 v[10:11], v[10:11], v[156:157]
	v_pk_add_f32 v[8:9], v[8:9], v[154:155]
	global_store_dwordx4 v[250:251], v[8:11], off offset:64
	s_waitcnt vmcnt(15)
	v_pk_add_f32 v[6:7], v[6:7], v[160:161]
	v_pk_add_f32 v[4:5], v[4:5], v[158:159]
	global_store_dwordx4 v[250:251], v[4:7], off offset:512
	s_waitcnt vmcnt(15)
	v_pk_add_f32 v[2:3], v[2:3], v[248:249]
	v_pk_add_f32 v[0:1], v[0:1], v[246:247]
	global_store_dwordx4 v[250:251], v[0:3], off offset:576
	s_cbranch_vccnz .LBB0_161
	s_andn2_b64 vcc, exec, s[76:77]
	s_cbranch_vccnz .LBB0_160
	s_barrier
	s_branch .LBB0_160

; template <int L, int N> DEVQ void filt_item(const Params& P, LAS unsigned char* lds, const float* H3v, int d, cf* specd, float* cornerd) {
;     ...
;     const float delta = fabsf(MIN_DECAY + (float)d * ((MAX_DECAY - MIN_DECAY) / 1023.0f));
;     const float invN = 1.0f / (float)N;
;     for (int k = tid; k < L; k += NTHR) {
;         asm volatile("" ::: "memory");
;         const f32x4* hr = (const f32x4*)(H3v + (size_t)k * 64);
;         f32x4 acc = (f32x4){0.f, 0.f, 0.f, 0.f};
;         f32x4 hv[16];
; #pragma unroll
;         for (int i4 = 0; i4 < 16; ++i4) hv[i4] = hr[i4];
.LBB0_588:
	s_or_b64 exec, exec, s[0:1]
	v_cmp_gt_i32_e32 vcc, s16, v64
	s_waitcnt lgkmcnt(0)
	s_barrier
	s_and_saveexec_b64 s[0:1], vcc
	s_cbranch_execz .LBB0_597
	s_waitcnt vmcnt(0)
	v_cvt_f32_i32_e32 v2, s10
	v_readlane_b32 s2, v253, 41
	v_lshlrev_b64 v[0:1], 8, v[64:65]
	v_mov_b32_e32 v3, 0xc0447cbd
	v_lshl_add_u32 v72, v64, 2, s2
	v_readlane_b32 s2, v255, 40
	v_readlane_b32 s3, v255, 41
	v_sub_u32_e32 v73, 0x2000, v64
	v_fmamk_f32 v74, v2, 0xbc44ade8, v3
	v_lshl_add_u64 v[66:67], s[2:3], 0, v[0:1]
	s_mov_b64 s[12:13], 0
	v_mov_b32_e32 v75, v64
	v_mbcnt_lo_u32_b32 v202, -1, 0
	v_mbcnt_hi_u32_b32 v202, -1, v202
	v_mul_u32_u24_e32 v203, 0xf0, v202
	v_sub_u32_e32 v248, 0x1000, v203
	v_sub_u32_e32 v246, 0x3000, v203
	v_ashrrev_i32_e32 v249, 31, v248
	v_ashrrev_i32_e32 v247, 31, v246
	v_and_b32_e32 v203, 15, v202
	v_lshl_add_u32 v203, v203, 6, 0
	v_add_u32_e32 v203, 0x20000, v203
	ds_read_b128 v[148:151], v203
	ds_read_b128 v[154:157], v203 offset:16
	ds_read_b128 v[158:161], v203 offset:32
	ds_read_b128 v[162:165], v203 offset:48
	v_lshrrev_b32_e32 v204, 6, v64
	v_cmp_lt_u32_e64 s[2:3], 5, v204
	v_lshl_add_u32 v204, v204, 10, 0
	v_mov_b32_e32 v205, 0x400
	v_add_u32_e32 v204, 0x20800, v204
	v_cndmask_b32_e64 v205, 0, v205, s[2:3]
	v_add_u32_e32 v204, v204, v205
	v_lshrrev_b32_e32 v205, 4, v202
	v_lshl_add_u32 v251, v205, 4, v204
	v_lshl_add_u32 v250, v202, 4, v204
	v_add_co_u32_e32 v226, vcc, 0x20000, v248
	s_nop 1
	v_addc_co_u32_e32 v227, vcc, 0, v249, vcc
	v_add_co_u32_e32 v228, vcc, 0x20000, v246
	s_nop 1
	v_addc_co_u32_e32 v229, vcc, 0, v247, vcc
	v_lshl_add_u64 v[198:199], v[66:67], 0, v[248:249]
	v_lshl_add_u64 v[200:201], v[66:67], 0, v[246:247]
	global_load_dwordx4 v[214:217], v[198:199], off offset:-4096
	global_load_dwordx4 v[218:221], v[198:199], off offset:-3072
	global_load_dwordx4 v[222:225], v[198:199], off offset:-2048
	global_load_dwordx4 v[12:15], v[198:199], off offset:-1024
	global_load_dwordx4 v[16:19], v[198:199], off offset:0
	global_load_dwordx4 v[20:23], v[198:199], off offset:1024
	global_load_dwordx4 v[24:27], v[198:199], off offset:2048
	global_load_dwordx4 v[28:31], v[198:199], off offset:3072
	global_load_dwordx4 v[32:35], v[200:201], off offset:-4096
	global_load_dwordx4 v[36:39], v[200:201], off offset:-3072
	global_load_dwordx4 v[40:43], v[200:201], off offset:-2048
	global_load_dwordx4 v[44:47], v[200:201], off offset:-1024
	global_load_dwordx4 v[48:51], v[200:201], off offset:0
	global_load_dwordx4 v[52:55], v[200:201], off offset:1024
	global_load_dwordx4 v[56:59], v[200:201], off offset:2048
	global_load_dwordx4 v[60:63], v[200:201], off offset:3072
	s_waitcnt lgkmcnt(0)
	s_branch .LBB0_591

; template <int L, int N> DEVQ void filt_item(const Params& P, LAS unsigned char* lds, const float* H3v, int d, cf* specd, float* cornerd) {
;     ...
;         const f32x4* hr = (const f32x4*)(H3v + (size_t)k * 64);
;         f32x4 acc = (f32x4){0.f, 0.f, 0.f, 0.f};
;         f32x4 hv[16];
; #pragma unroll
;         for (int i4 = 0; i4 < 16; ++i4) hv[i4] = hr[i4];
; #pragma unroll
;         for (int i4 = 0; i4 < 16; ++i4) { if ((i4 & 3) == 0) asm volatile("" ::: "memory");
;             acc += hv[i4].x * wc4[4 * i4] + hv[i4].y * wc4[4 * i4 + 1] + hv[i4].z * wc4[4 * i4 + 2] + hv[i4].w * wc4[4 * i4 + 3]; }
.LBB0_591:
	s_mov_b64 s[14:15], exec
	s_mov_b64 exec, -1
	v_lshl_add_u64 v[198:199], v[66:67], 0, v[226:227]
	v_lshl_add_u64 v[200:201], v[66:67], 0, v[228:229]
	s_mov_b32 s2, 0x10001
	s_mov_b32 s3, 0x10001
	s_waitcnt vmcnt(15)
	v_mul_f32_e32 v194, v214, v148
	v_mul_f32_e32 v195, v214, v149
	v_mul_f32_e32 v196, v214, v150
	v_mul_f32_e32 v197, v214, v151
	v_fmac_f32_e32 v194, v215, v154
	v_fmac_f32_e32 v195, v215, v155
	v_fmac_f32_e32 v196, v215, v156
	v_fmac_f32_e32 v197, v215, v157
	v_fmac_f32_e32 v194, v216, v158
	v_fmac_f32_e32 v195, v216, v159
	v_fmac_f32_e32 v196, v216, v160
	v_fmac_f32_e32 v197, v216, v161
	v_fmac_f32_e32 v194, v217, v162
	v_fmac_f32_e32 v195, v217, v163
	v_fmac_f32_e32 v196, v217, v164
	v_fmac_f32_e32 v197, v217, v165
	v_add_f32_dpp v194, v194, v194 row_ror:8 row_mask:0xf bank_mask:0xf
	v_add_f32_dpp v195, v195, v195 row_ror:8 row_mask:0xf bank_mask:0xf
	v_add_f32_dpp v196, v196, v196 row_ror:8 row_mask:0xf bank_mask:0xf
	v_add_f32_dpp v197, v197, v197 row_ror:8 row_mask:0xf bank_mask:0xf
	v_add_f32_dpp v194, v194, v194 row_ror:4 row_mask:0xf bank_mask:0xf
	v_add_f32_dpp v195, v195, v195 row_ror:4 row_mask:0xf bank_mask:0xf
	v_add_f32_dpp v196, v196, v196 row_ror:4 row_mask:0xf bank_mask:0xf
	v_add_f32_dpp v197, v197, v197 row_ror:4 row_mask:0xf bank_mask:0xf
	v_add_f32_dpp v194, v194, v194 row_ror:2 row_mask:0xf bank_mask:0xf
	v_add_f32_dpp v195, v195, v195 row_ror:2 row_mask:0xf bank_mask:0xf
	v_add_f32_dpp v196, v196, v196 row_ror:2 row_mask:0xf bank_mask:0xf
	v_add_f32_dpp v197, v197, v197 row_ror:2 row_mask:0xf bank_mask:0xf
	v_add_f32_dpp v194, v194, v194 row_ror:1 row_mask:0xf bank_mask:0xf
	v_add_f32_dpp v195, v195, v195 row_ror:1 row_mask:0xf bank_mask:0xf
	v_add_f32_dpp v196, v196, v196 row_ror:1 row_mask:0xf bank_mask:0xf
	v_add_f32_dpp v197, v197, v197 row_ror:1 row_mask:0xf bank_mask:0xf
	s_mov_b64 exec, s[2:3]
	ds_write_b128 v251, v[194:197]
	s_mov_b64 exec, -1
	global_load_dwordx4 v[214:217], v[198:199], off offset:-4096
	s_waitcnt vmcnt(15)
	v_mul_f32_e32 v210, v218, v148
	v_mul_f32_e32 v211, v218, v149
	v_mul_f32_e32 v212, v218, v150
	v_mul_f32_e32 v213, v218, v151
	v_fmac_f32_e32 v210, v219, v154
	v_fmac_f32_e32 v211, v219, v155
	v_fmac_f32_e32 v212, v219, v156
	v_fmac_f32_e32 v213, v219, v157
	v_fmac_f32_e32 v210, v220, v158
	v_fmac_f32_e32 v211, v220, v159
	v_fmac_f32_e32 v212, v220, v160
	v_fmac_f32_e32 v213, v220, v161
	v_fmac_f32_e32 v210, v221, v162
	v_fmac_f32_e32 v211, v221, v163
	v_fmac_f32_e32 v212, v221, v164
	v_fmac_f32_e32 v213, v221, v165
	v_add_f32_dpp v210, v210, v210 row_ror:8 row_mask:0xf bank_mask:0xf
	v_add_f32_dpp v211, v211, v211 row_ror:8 row_mask:0xf bank_mask:0xf
	v_add_f32_dpp v212, v212, v212 row_ror:8 row_mask:0xf bank_mask:0xf
	v_add_f32_dpp v213, v213, v213 row_ror:8 row_mask:0xf bank_mask:0xf
	v_add_f32_dpp v210, v210, v210 row_ror:4 row_mask:0xf bank_mask:0xf
	v_add_f32_dpp v211, v211, v211 row_ror:4 row_mask:0xf bank_mask:0xf
	v_add_f32_dpp v212, v212, v212 row_ror:4 row_mask:0xf bank_mask:0xf
	v_add_f32_dpp v213, v213, v213 row_ror:4 row_mask:0xf bank_mask:0xf
	v_add_f32_dpp v210, v210, v210 row_ror:2 row_mask:0xf bank_mask:0xf
	v_add_f32_dpp v211, v211, v211 row_ror:2 row_mask:0xf bank_mask:0xf
	v_add_f32_dpp v212, v212, v212 row_ror:2 row_mask:0xf bank_mask:0xf
	v_add_f32_dpp v213, v213, v213 row_ror:2 row_mask:0xf bank_mask:0xf
	v_add_f32_dpp v210, v210, v210 row_ror:1 row_mask:0xf bank_mask:0xf
	v_add_f32_dpp v211, v211, v211 row_ror:1 row_mask:0xf bank_mask:0xf
	v_add_f32_dpp v212, v212, v212 row_ror:1 row_mask:0xf bank_mask:0xf
	v_add_f32_dpp v213, v213, v213 row_ror:1 row_mask:0xf bank_mask:0xf
	s_mov_b64 exec, s[2:3]
	ds_write_b128 v251, v[210:213] offset:64
	s_mov_b64 exec, -1
	global_load_dwordx4 v[218:221], v[198:199], off offset:-3072
	s_waitcnt vmcnt(15)
	v_mul_f32_e32 v194, v222, v148
	v_mul_f32_e32 v195, v222, v149
	v_mul_f32_e32 v196, v222, v150
	v_mul_f32_e32 v197, v222, v151
	v_fmac_f32_e32 v194, v223, v154
	v_fmac_f32_e32 v195, v223, v155
	v_fmac_f32_e32 v196, v223, v156
	v_fmac_f32_e32 v197, v223, v157
	v_fmac_f32_e32 v194, v224, v158
	v_fmac_f32_e32 v195, v224, v159
	v_fmac_f32_e32 v196, v224, v160
	v_fmac_f32_e32 v197, v224, v161
	v_fmac_f32_e32 v194, v225, v162
	v_fmac_f32_e32 v195, v225, v163
	v_fmac_f32_e32 v196, v225, v164
	v_fmac_f32_e32 v197, v225, v165
	v_add_f32_dpp v194, v194, v194 row_ror:8 row_mask:0xf bank_mask:0xf
	v_add_f32_dpp v195, v195, v195 row_ror:8 row_mask:0xf bank_mask:0xf
	v_add_f32_dpp v196, v196, v196 row_ror:8 row_mask:0xf bank_mask:0xf
	v_add_f32_dpp v197, v197, v197 row_ror:8 row_mask:0xf bank_mask:0xf
	v_add_f32_dpp v194, v194, v194 row_ror:4 row_mask:0xf bank_mask:0xf
	v_add_f32_dpp v195, v195, v195 row_ror:4 row_mask:0xf bank_mask:0xf
	v_add_f32_dpp v196, v196, v196 row_ror:4 row_mask:0xf bank_mask:0xf
	v_add_f32_dpp v197, v197, v197 row_ror:4 row_mask:0xf bank_mask:0xf
	v_add_f32_dpp v194, v194, v194 row_ror:2 row_mask:0xf bank_mask:0xf
	v_add_f32_dpp v195, v195, v195 row_ror:2 row_mask:0xf bank_mask:0xf
	v_add_f32_dpp v196, v196, v196 row_ror:2 row_mask:0xf bank_mask:0xf
	v_add_f32_dpp v197, v197, v197 row_ror:2 row_mask:0xf bank_mask:0xf
	v_add_f32_dpp v194, v194, v194 row_ror:1 row_mask:0xf bank_mask:0xf
	v_add_f32_dpp v195, v195, v195 row_ror:1 row_mask:0xf bank_mask:0xf
	v_add_f32_dpp v196, v196, v196 row_ror:1 row_mask:0xf bank_mask:0xf
	v_add_f32_dpp v197, v197, v197 row_ror:1 row_mask:0xf bank_mask:0xf
	s_mov_b64 exec, s[2:3]
	ds_write_b128 v251, v[194:197] offset:128
	s_mov_b64 exec, -1
	global_load_dwordx4 v[222:225], v[198:199], off offset:-2048
	s_waitcnt vmcnt(15)
; template <int L, int N> DEVQ void filt_item(const Params& P, LAS unsigned char* lds, const float* H3v, int d, cf* specd, float* cornerd) {
;     ...
;         for (int i4 = 0; i4 < 16; ++i4) hv[i4] = hr[i4];
; #pragma unroll
;         for (int i4 = 0; i4 < 16; ++i4) { if ((i4 & 3) == 0) asm volatile("" ::: "memory");
;             acc += hv[i4].x * wc4[4 * i4] + hv[i4].y * wc4[4 * i4 + 1] + hv[i4].z * wc4[4 * i4 + 2] + hv[i4].w * wc4[4 * i4 + 3]; }
	v_mul_f32_e32 v210, v12, v148
	v_mul_f32_e32 v211, v12, v149
	v_mul_f32_e32 v212, v12, v150
	v_mul_f32_e32 v213, v12, v151
	v_fmac_f32_e32 v210, v13, v154
	v_fmac_f32_e32 v211, v13, v155
	v_fmac_f32_e32 v212, v13, v156
	v_fmac_f32_e32 v213, v13, v157
	v_fmac_f32_e32 v210, v14, v158
	v_fmac_f32_e32 v211, v14, v159
	v_fmac_f32_e32 v212, v14, v160
	v_fmac_f32_e32 v213, v14, v161
	v_fmac_f32_e32 v210, v15, v162
	v_fmac_f32_e32 v211, v15, v163
	v_fmac_f32_e32 v212, v15, v164
	v_fmac_f32_e32 v213, v15, v165
	v_add_f32_dpp v210, v210, v210 row_ror:8 row_mask:0xf bank_mask:0xf
	v_add_f32_dpp v211, v211, v211 row_ror:8 row_mask:0xf bank_mask:0xf
	v_add_f32_dpp v212, v212, v212 row_ror:8 row_mask:0xf bank_mask:0xf
	v_add_f32_dpp v213, v213, v213 row_ror:8 row_mask:0xf bank_mask:0xf
	v_add_f32_dpp v210, v210, v210 row_ror:4 row_mask:0xf bank_mask:0xf
	v_add_f32_dpp v211, v211, v211 row_ror:4 row_mask:0xf bank_mask:0xf
	v_add_f32_dpp v212, v212, v212 row_ror:4 row_mask:0xf bank_mask:0xf
	v_add_f32_dpp v213, v213, v213 row_ror:4 row_mask:0xf bank_mask:0xf
	v_add_f32_dpp v210, v210, v210 row_ror:2 row_mask:0xf bank_mask:0xf
	v_add_f32_dpp v211, v211, v211 row_ror:2 row_mask:0xf bank_mask:0xf
	v_add_f32_dpp v212, v212, v212 row_ror:2 row_mask:0xf bank_mask:0xf
	v_add_f32_dpp v213, v213, v213 row_ror:2 row_mask:0xf bank_mask:0xf
	v_add_f32_dpp v210, v210, v210 row_ror:1 row_mask:0xf bank_mask:0xf
	v_add_f32_dpp v211, v211, v211 row_ror:1 row_mask:0xf bank_mask:0xf
	v_add_f32_dpp v212, v212, v212 row_ror:1 row_mask:0xf bank_mask:0xf
	v_add_f32_dpp v213, v213, v213 row_ror:1 row_mask:0xf bank_mask:0xf
	s_mov_b64 exec, s[2:3]
	ds_write_b128 v251, v[210:213] offset:192
	s_mov_b64 exec, -1
	global_load_dwordx4 v[12:15], v[198:199], off offset:-1024
	s_waitcnt vmcnt(15)
	v_mul_f32_e32 v194, v16, v148
	v_mul_f32_e32 v195, v16, v149
	v_mul_f32_e32 v196, v16, v150
	v_mul_f32_e32 v197, v16, v151
	v_fmac_f32_e32 v194, v17, v154
	v_fmac_f32_e32 v195, v17, v155
	v_fmac_f32_e32 v196, v17, v156
	v_fmac_f32_e32 v197, v17, v157
	v_fmac_f32_e32 v194, v18, v158
	v_fmac_f32_e32 v195, v18, v159
	v_fmac_f32_e32 v196, v18, v160
	v_fmac_f32_e32 v197, v18, v161
	v_fmac_f32_e32 v194, v19, v162
	v_fmac_f32_e32 v195, v19, v163
	v_fmac_f32_e32 v196, v19, v164
	v_fmac_f32_e32 v197, v19, v165
	v_add_f32_dpp v194, v194, v194 row_ror:8 row_mask:0xf bank_mask:0xf
	v_add_f32_dpp v195, v195, v195 row_ror:8 row_mask:0xf bank_mask:0xf
	v_add_f32_dpp v196, v196, v196 row_ror:8 row_mask:0xf bank_mask:0xf
	v_add_f32_dpp v197, v197, v197 row_ror:8 row_mask:0xf bank_mask:0xf
	v_add_f32_dpp v194, v194, v194 row_ror:4 row_mask:0xf bank_mask:0xf
	v_add_f32_dpp v195, v195, v195 row_ror:4 row_mask:0xf bank_mask:0xf
	v_add_f32_dpp v196, v196, v196 row_ror:4 row_mask:0xf bank_mask:0xf
	v_add_f32_dpp v197, v197, v197 row_ror:4 row_mask:0xf bank_mask:0xf
	v_add_f32_dpp v194, v194, v194 row_ror:2 row_mask:0xf bank_mask:0xf
	v_add_f32_dpp v195, v195, v195 row_ror:2 row_mask:0xf bank_mask:0xf
	v_add_f32_dpp v196, v196, v196 row_ror:2 row_mask:0xf bank_mask:0xf
	v_add_f32_dpp v197, v197, v197 row_ror:2 row_mask:0xf bank_mask:0xf
	v_add_f32_dpp v194, v194, v194 row_ror:1 row_mask:0xf bank_mask:0xf
	v_add_f32_dpp v195, v195, v195 row_ror:1 row_mask:0xf bank_mask:0xf
	v_add_f32_dpp v196, v196, v196 row_ror:1 row_mask:0xf bank_mask:0xf
	v_add_f32_dpp v197, v197, v197 row_ror:1 row_mask:0xf bank_mask:0xf
	s_mov_b64 exec, s[2:3]
	ds_write_b128 v251, v[194:197] offset:256
	s_mov_b64 exec, -1
	global_load_dwordx4 v[16:19], v[198:199], off offset:0
	s_waitcnt vmcnt(15)
	v_mul_f32_e32 v210, v20, v148
	v_mul_f32_e32 v211, v20, v149
	v_mul_f32_e32 v212, v20, v150
	v_mul_f32_e32 v213, v20, v151
	v_fmac_f32_e32 v210, v21, v154
	v_fmac_f32_e32 v211, v21, v155
	v_fmac_f32_e32 v212, v21, v156
	v_fmac_f32_e32 v213, v21, v157
	v_fmac_f32_e32 v210, v22, v158
	v_fmac_f32_e32 v211, v22, v159
	v_fmac_f32_e32 v212, v22, v160
	v_fmac_f32_e32 v213, v22, v161
	v_fmac_f32_e32 v210, v23, v162
	v_fmac_f32_e32 v211, v23, v163
	v_fmac_f32_e32 v212, v23, v164
	v_fmac_f32_e32 v213, v23, v165
	v_add_f32_dpp v210, v210, v210 row_ror:8 row_mask:0xf bank_mask:0xf
	v_add_f32_dpp v211, v211, v211 row_ror:8 row_mask:0xf bank_mask:0xf
	v_add_f32_dpp v212, v212, v212 row_ror:8 row_mask:0xf bank_mask:0xf
	v_add_f32_dpp v213, v213, v213 row_ror:8 row_mask:0xf bank_mask:0xf
	v_add_f32_dpp v210, v210, v210 row_ror:4 row_mask:0xf bank_mask:0xf
	v_add_f32_dpp v211, v211, v211 row_ror:4 row_mask:0xf bank_mask:0xf
	v_add_f32_dpp v212, v212, v212 row_ror:4 row_mask:0xf bank_mask:0xf
	v_add_f32_dpp v213, v213, v213 row_ror:4 row_mask:0xf bank_mask:0xf
	v_add_f32_dpp v210, v210, v210 row_ror:2 row_mask:0xf bank_mask:0xf
	v_add_f32_dpp v211, v211, v211 row_ror:2 row_mask:0xf bank_mask:0xf
	v_add_f32_dpp v212, v212, v212 row_ror:2 row_mask:0xf bank_mask:0xf
	v_add_f32_dpp v213, v213, v213 row_ror:2 row_mask:0xf bank_mask:0xf
	v_add_f32_dpp v210, v210, v210 row_ror:1 row_mask:0xf bank_mask:0xf
	v_add_f32_dpp v211, v211, v211 row_ror:1 row_mask:0xf bank_mask:0xf
	v_add_f32_dpp v212, v212, v212 row_ror:1 row_mask:0xf bank_mask:0xf
	v_add_f32_dpp v213, v213, v213 row_ror:1 row_mask:0xf bank_mask:0xf
	s_mov_b64 exec, s[2:3]
	ds_write_b128 v251, v[210:213] offset:320
	s_mov_b64 exec, -1
	global_load_dwordx4 v[20:23], v[198:199], off offset:1024
	s_waitcnt vmcnt(15)
; template <int L, int N> DEVQ void filt_item(const Params& P, LAS unsigned char* lds, const float* H3v, int d, cf* specd, float* cornerd) {
;     ...
;     for (int k = tid; k < L; k += NTHR) {
;         asm volatile("" ::: "memory");
;         const f32x4* hr = (const f32x4*)(H3v + (size_t)k * 64);
;         f32x4 acc = (f32x4){0.f, 0.f, 0.f, 0.f};
;         f32x4 hv[16];
; #pragma unroll
;         for (int i4 = 0; i4 < 16; ++i4) hv[i4] = hr[i4];
; #pragma unroll
;         for (int i4 = 0; i4 < 16; ++i4) { if ((i4 & 3) == 0) asm volatile("" ::: "memory");
;             acc += hv[i4].x * wc4[4 * i4] + hv[i4].y * wc4[4 * i4 + 1] + hv[i4].z * wc4[4 * i4 + 2] + hv[i4].w * wc4[4 * i4 + 3]; }
	v_mul_f32_e32 v194, v24, v148
	v_mul_f32_e32 v195, v24, v149
	v_mul_f32_e32 v196, v24, v150
	v_mul_f32_e32 v197, v24, v151
	v_fmac_f32_e32 v194, v25, v154
	v_fmac_f32_e32 v195, v25, v155
	v_fmac_f32_e32 v196, v25, v156
	v_fmac_f32_e32 v197, v25, v157
	v_fmac_f32_e32 v194, v26, v158
	v_fmac_f32_e32 v195, v26, v159
	v_fmac_f32_e32 v196, v26, v160
	v_fmac_f32_e32 v197, v26, v161
	v_fmac_f32_e32 v194, v27, v162
	v_fmac_f32_e32 v195, v27, v163
	v_fmac_f32_e32 v196, v27, v164
	v_fmac_f32_e32 v197, v27, v165
	v_add_f32_dpp v194, v194, v194 row_ror:8 row_mask:0xf bank_mask:0xf
	v_add_f32_dpp v195, v195, v195 row_ror:8 row_mask:0xf bank_mask:0xf
	v_add_f32_dpp v196, v196, v196 row_ror:8 row_mask:0xf bank_mask:0xf
	v_add_f32_dpp v197, v197, v197 row_ror:8 row_mask:0xf bank_mask:0xf
	v_add_f32_dpp v194, v194, v194 row_ror:4 row_mask:0xf bank_mask:0xf
	v_add_f32_dpp v195, v195, v195 row_ror:4 row_mask:0xf bank_mask:0xf
	v_add_f32_dpp v196, v196, v196 row_ror:4 row_mask:0xf bank_mask:0xf
	v_add_f32_dpp v197, v197, v197 row_ror:4 row_mask:0xf bank_mask:0xf
	v_add_f32_dpp v194, v194, v194 row_ror:2 row_mask:0xf bank_mask:0xf
	v_add_f32_dpp v195, v195, v195 row_ror:2 row_mask:0xf bank_mask:0xf
	v_add_f32_dpp v196, v196, v196 row_ror:2 row_mask:0xf bank_mask:0xf
	v_add_f32_dpp v197, v197, v197 row_ror:2 row_mask:0xf bank_mask:0xf
	v_add_f32_dpp v194, v194, v194 row_ror:1 row_mask:0xf bank_mask:0xf
	v_add_f32_dpp v195, v195, v195 row_ror:1 row_mask:0xf bank_mask:0xf
	v_add_f32_dpp v196, v196, v196 row_ror:1 row_mask:0xf bank_mask:0xf
	v_add_f32_dpp v197, v197, v197 row_ror:1 row_mask:0xf bank_mask:0xf
	s_mov_b64 exec, s[2:3]
	ds_write_b128 v251, v[194:197] offset:384
	s_mov_b64 exec, -1
	global_load_dwordx4 v[24:27], v[198:199], off offset:2048
	s_waitcnt vmcnt(15)
	v_mul_f32_e32 v210, v28, v148
	v_mul_f32_e32 v211, v28, v149
	v_mul_f32_e32 v212, v28, v150
	v_mul_f32_e32 v213, v28, v151
	v_fmac_f32_e32 v210, v29, v154
	v_fmac_f32_e32 v211, v29, v155
	v_fmac_f32_e32 v212, v29, v156
	v_fmac_f32_e32 v213, v29, v157
	v_fmac_f32_e32 v210, v30, v158
	v_fmac_f32_e32 v211, v30, v159
	v_fmac_f32_e32 v212, v30, v160
	v_fmac_f32_e32 v213, v30, v161
	v_fmac_f32_e32 v210, v31, v162
	v_fmac_f32_e32 v211, v31, v163
	v_fmac_f32_e32 v212, v31, v164
	v_fmac_f32_e32 v213, v31, v165
	v_add_f32_dpp v210, v210, v210 row_ror:8 row_mask:0xf bank_mask:0xf
	v_add_f32_dpp v211, v211, v211 row_ror:8 row_mask:0xf bank_mask:0xf
	v_add_f32_dpp v212, v212, v212 row_ror:8 row_mask:0xf bank_mask:0xf
	v_add_f32_dpp v213, v213, v213 row_ror:8 row_mask:0xf bank_mask:0xf
	v_add_f32_dpp v210, v210, v210 row_ror:4 row_mask:0xf bank_mask:0xf
	v_add_f32_dpp v211, v211, v211 row_ror:4 row_mask:0xf bank_mask:0xf
	v_add_f32_dpp v212, v212, v212 row_ror:4 row_mask:0xf bank_mask:0xf
	v_add_f32_dpp v213, v213, v213 row_ror:4 row_mask:0xf bank_mask:0xf
	v_add_f32_dpp v210, v210, v210 row_ror:2 row_mask:0xf bank_mask:0xf
	v_add_f32_dpp v211, v211, v211 row_ror:2 row_mask:0xf bank_mask:0xf
	v_add_f32_dpp v212, v212, v212 row_ror:2 row_mask:0xf bank_mask:0xf
	v_add_f32_dpp v213, v213, v213 row_ror:2 row_mask:0xf bank_mask:0xf
	v_add_f32_dpp v210, v210, v210 row_ror:1 row_mask:0xf bank_mask:0xf
	v_add_f32_dpp v211, v211, v211 row_ror:1 row_mask:0xf bank_mask:0xf
	v_add_f32_dpp v212, v212, v212 row_ror:1 row_mask:0xf bank_mask:0xf
	v_add_f32_dpp v213, v213, v213 row_ror:1 row_mask:0xf bank_mask:0xf
	s_mov_b64 exec, s[2:3]
	ds_write_b128 v251, v[210:213] offset:448
	s_mov_b64 exec, -1
	global_load_dwordx4 v[28:31], v[198:199], off offset:3072
	s_waitcnt vmcnt(15)
	v_mul_f32_e32 v194, v32, v148
	v_mul_f32_e32 v195, v32, v149
	v_mul_f32_e32 v196, v32, v150
	v_mul_f32_e32 v197, v32, v151
	v_fmac_f32_e32 v194, v33, v154
	v_fmac_f32_e32 v195, v33, v155
	v_fmac_f32_e32 v196, v33, v156
	v_fmac_f32_e32 v197, v33, v157
	v_fmac_f32_e32 v194, v34, v158
	v_fmac_f32_e32 v195, v34, v159
	v_fmac_f32_e32 v196, v34, v160
	v_fmac_f32_e32 v197, v34, v161
	v_fmac_f32_e32 v194, v35, v162
	v_fmac_f32_e32 v195, v35, v163
	v_fmac_f32_e32 v196, v35, v164
	v_fmac_f32_e32 v197, v35, v165
	v_add_f32_dpp v194, v194, v194 row_ror:8 row_mask:0xf bank_mask:0xf
	v_add_f32_dpp v195, v195, v195 row_ror:8 row_mask:0xf bank_mask:0xf
	v_add_f32_dpp v196, v196, v196 row_ror:8 row_mask:0xf bank_mask:0xf
	v_add_f32_dpp v197, v197, v197 row_ror:8 row_mask:0xf bank_mask:0xf
	v_add_f32_dpp v194, v194, v194 row_ror:4 row_mask:0xf bank_mask:0xf
	v_add_f32_dpp v195, v195, v195 row_ror:4 row_mask:0xf bank_mask:0xf
	v_add_f32_dpp v196, v196, v196 row_ror:4 row_mask:0xf bank_mask:0xf
	v_add_f32_dpp v197, v197, v197 row_ror:4 row_mask:0xf bank_mask:0xf
	v_add_f32_dpp v194, v194, v194 row_ror:2 row_mask:0xf bank_mask:0xf
	v_add_f32_dpp v195, v195, v195 row_ror:2 row_mask:0xf bank_mask:0xf
	v_add_f32_dpp v196, v196, v196 row_ror:2 row_mask:0xf bank_mask:0xf
	v_add_f32_dpp v197, v197, v197 row_ror:2 row_mask:0xf bank_mask:0xf
	v_add_f32_dpp v194, v194, v194 row_ror:1 row_mask:0xf bank_mask:0xf
	v_add_f32_dpp v195, v195, v195 row_ror:1 row_mask:0xf bank_mask:0xf
	v_add_f32_dpp v196, v196, v196 row_ror:1 row_mask:0xf bank_mask:0xf
	v_add_f32_dpp v197, v197, v197 row_ror:1 row_mask:0xf bank_mask:0xf
	s_mov_b64 exec, s[2:3]
	ds_write_b128 v251, v[194:197] offset:512
	s_mov_b64 exec, -1
	global_load_dwordx4 v[32:35], v[200:201], off offset:-4096
	s_waitcnt vmcnt(15)
; template <int L, int N> DEVQ void filt_item(const Params& P, LAS unsigned char* lds, const float* H3v, int d, cf* specd, float* cornerd) {
;     ...
;     for (int k = tid; k < L; k += NTHR) {
;         asm volatile("" ::: "memory");
;         const f32x4* hr = (const f32x4*)(H3v + (size_t)k * 64);
;         f32x4 acc = (f32x4){0.f, 0.f, 0.f, 0.f};
;         f32x4 hv[16];
; #pragma unroll
;         for (int i4 = 0; i4 < 16; ++i4) hv[i4] = hr[i4];
; #pragma unroll
;         for (int i4 = 0; i4 < 16; ++i4) { if ((i4 & 3) == 0) asm volatile("" ::: "memory");
;             acc += hv[i4].x * wc4[4 * i4] + hv[i4].y * wc4[4 * i4 + 1] + hv[i4].z * wc4[4 * i4 + 2] + hv[i4].w * wc4[4 * i4 + 3]; }
	v_mul_f32_e32 v210, v36, v148
	v_mul_f32_e32 v211, v36, v149
	v_mul_f32_e32 v212, v36, v150
	v_mul_f32_e32 v213, v36, v151
	v_fmac_f32_e32 v210, v37, v154
	v_fmac_f32_e32 v211, v37, v155
	v_fmac_f32_e32 v212, v37, v156
	v_fmac_f32_e32 v213, v37, v157
	v_fmac_f32_e32 v210, v38, v158
	v_fmac_f32_e32 v211, v38, v159
	v_fmac_f32_e32 v212, v38, v160
	v_fmac_f32_e32 v213, v38, v161
	v_fmac_f32_e32 v210, v39, v162
	v_fmac_f32_e32 v211, v39, v163
	v_fmac_f32_e32 v212, v39, v164
	v_fmac_f32_e32 v213, v39, v165
	v_add_f32_dpp v210, v210, v210 row_ror:8 row_mask:0xf bank_mask:0xf
	v_add_f32_dpp v211, v211, v211 row_ror:8 row_mask:0xf bank_mask:0xf
	v_add_f32_dpp v212, v212, v212 row_ror:8 row_mask:0xf bank_mask:0xf
	v_add_f32_dpp v213, v213, v213 row_ror:8 row_mask:0xf bank_mask:0xf
	v_add_f32_dpp v210, v210, v210 row_ror:4 row_mask:0xf bank_mask:0xf
	v_add_f32_dpp v211, v211, v211 row_ror:4 row_mask:0xf bank_mask:0xf
	v_add_f32_dpp v212, v212, v212 row_ror:4 row_mask:0xf bank_mask:0xf
	v_add_f32_dpp v213, v213, v213 row_ror:4 row_mask:0xf bank_mask:0xf
	v_add_f32_dpp v210, v210, v210 row_ror:2 row_mask:0xf bank_mask:0xf
	v_add_f32_dpp v211, v211, v211 row_ror:2 row_mask:0xf bank_mask:0xf
	v_add_f32_dpp v212, v212, v212 row_ror:2 row_mask:0xf bank_mask:0xf
	v_add_f32_dpp v213, v213, v213 row_ror:2 row_mask:0xf bank_mask:0xf
	v_add_f32_dpp v210, v210, v210 row_ror:1 row_mask:0xf bank_mask:0xf
	v_add_f32_dpp v211, v211, v211 row_ror:1 row_mask:0xf bank_mask:0xf
	v_add_f32_dpp v212, v212, v212 row_ror:1 row_mask:0xf bank_mask:0xf
	v_add_f32_dpp v213, v213, v213 row_ror:1 row_mask:0xf bank_mask:0xf
	s_mov_b64 exec, s[2:3]
	ds_write_b128 v251, v[210:213] offset:576
	s_mov_b64 exec, -1
	global_load_dwordx4 v[36:39], v[200:201], off offset:-3072
	s_waitcnt vmcnt(15)
	v_mul_f32_e32 v194, v40, v148
	v_mul_f32_e32 v195, v40, v149
	v_mul_f32_e32 v196, v40, v150
	v_mul_f32_e32 v197, v40, v151
	v_fmac_f32_e32 v194, v41, v154
	v_fmac_f32_e32 v195, v41, v155
	v_fmac_f32_e32 v196, v41, v156
	v_fmac_f32_e32 v197, v41, v157
	v_fmac_f32_e32 v194, v42, v158
	v_fmac_f32_e32 v195, v42, v159
	v_fmac_f32_e32 v196, v42, v160
	v_fmac_f32_e32 v197, v42, v161
	v_fmac_f32_e32 v194, v43, v162
	v_fmac_f32_e32 v195, v43, v163
	v_fmac_f32_e32 v196, v43, v164
	v_fmac_f32_e32 v197, v43, v165
	v_add_f32_dpp v194, v194, v194 row_ror:8 row_mask:0xf bank_mask:0xf
	v_add_f32_dpp v195, v195, v195 row_ror:8 row_mask:0xf bank_mask:0xf
	v_add_f32_dpp v196, v196, v196 row_ror:8 row_mask:0xf bank_mask:0xf
	v_add_f32_dpp v197, v197, v197 row_ror:8 row_mask:0xf bank_mask:0xf
	v_add_f32_dpp v194, v194, v194 row_ror:4 row_mask:0xf bank_mask:0xf
	v_add_f32_dpp v195, v195, v195 row_ror:4 row_mask:0xf bank_mask:0xf
	v_add_f32_dpp v196, v196, v196 row_ror:4 row_mask:0xf bank_mask:0xf
	v_add_f32_dpp v197, v197, v197 row_ror:4 row_mask:0xf bank_mask:0xf
	v_add_f32_dpp v194, v194, v194 row_ror:2 row_mask:0xf bank_mask:0xf
	v_add_f32_dpp v195, v195, v195 row_ror:2 row_mask:0xf bank_mask:0xf
	v_add_f32_dpp v196, v196, v196 row_ror:2 row_mask:0xf bank_mask:0xf
	v_add_f32_dpp v197, v197, v197 row_ror:2 row_mask:0xf bank_mask:0xf
	v_add_f32_dpp v194, v194, v194 row_ror:1 row_mask:0xf bank_mask:0xf
	v_add_f32_dpp v195, v195, v195 row_ror:1 row_mask:0xf bank_mask:0xf
	v_add_f32_dpp v196, v196, v196 row_ror:1 row_mask:0xf bank_mask:0xf
	v_add_f32_dpp v197, v197, v197 row_ror:1 row_mask:0xf bank_mask:0xf
	s_mov_b64 exec, s[2:3]
	ds_write_b128 v251, v[194:197] offset:640
	s_mov_b64 exec, -1
	global_load_dwordx4 v[40:43], v[200:201], off offset:-2048
	s_waitcnt vmcnt(15)
	v_mul_f32_e32 v210, v44, v148
	v_mul_f32_e32 v211, v44, v149
	v_mul_f32_e32 v212, v44, v150
	v_mul_f32_e32 v213, v44, v151
	v_fmac_f32_e32 v210, v45, v154
	v_fmac_f32_e32 v211, v45, v155
	v_fmac_f32_e32 v212, v45, v156
	v_fmac_f32_e32 v213, v45, v157
	v_fmac_f32_e32 v210, v46, v158
	v_fmac_f32_e32 v211, v46, v159
	v_fmac_f32_e32 v212, v46, v160
	v_fmac_f32_e32 v213, v46, v161
	v_fmac_f32_e32 v210, v47, v162
	v_fmac_f32_e32 v211, v47, v163
	v_fmac_f32_e32 v212, v47, v164
	v_fmac_f32_e32 v213, v47, v165
	v_add_f32_dpp v210, v210, v210 row_ror:8 row_mask:0xf bank_mask:0xf
	v_add_f32_dpp v211, v211, v211 row_ror:8 row_mask:0xf bank_mask:0xf
	v_add_f32_dpp v212, v212, v212 row_ror:8 row_mask:0xf bank_mask:0xf
	v_add_f32_dpp v213, v213, v213 row_ror:8 row_mask:0xf bank_mask:0xf
	v_add_f32_dpp v210, v210, v210 row_ror:4 row_mask:0xf bank_mask:0xf
	v_add_f32_dpp v211, v211, v211 row_ror:4 row_mask:0xf bank_mask:0xf
	v_add_f32_dpp v212, v212, v212 row_ror:4 row_mask:0xf bank_mask:0xf
	v_add_f32_dpp v213, v213, v213 row_ror:4 row_mask:0xf bank_mask:0xf
	v_add_f32_dpp v210, v210, v210 row_ror:2 row_mask:0xf bank_mask:0xf
	v_add_f32_dpp v211, v211, v211 row_ror:2 row_mask:0xf bank_mask:0xf
	v_add_f32_dpp v212, v212, v212 row_ror:2 row_mask:0xf bank_mask:0xf
	v_add_f32_dpp v213, v213, v213 row_ror:2 row_mask:0xf bank_mask:0xf
	v_add_f32_dpp v210, v210, v210 row_ror:1 row_mask:0xf bank_mask:0xf
	v_add_f32_dpp v211, v211, v211 row_ror:1 row_mask:0xf bank_mask:0xf
	v_add_f32_dpp v212, v212, v212 row_ror:1 row_mask:0xf bank_mask:0xf
	v_add_f32_dpp v213, v213, v213 row_ror:1 row_mask:0xf bank_mask:0xf
	s_mov_b64 exec, s[2:3]
	ds_write_b128 v251, v[210:213] offset:704
	s_mov_b64 exec, -1
	global_load_dwordx4 v[44:47], v[200:201], off offset:-1024
	s_waitcnt vmcnt(15)
; template <int L, int N> DEVQ void filt_item(const Params& P, LAS unsigned char* lds, const float* H3v, int d, cf* specd, float* cornerd) {
;     ...
;     for (int k = tid; k < L; k += NTHR) {
;         asm volatile("" ::: "memory");
;         const f32x4* hr = (const f32x4*)(H3v + (size_t)k * 64);
;         f32x4 acc = (f32x4){0.f, 0.f, 0.f, 0.f};
;         f32x4 hv[16];
; #pragma unroll
;         for (int i4 = 0; i4 < 16; ++i4) hv[i4] = hr[i4];
; #pragma unroll
;         for (int i4 = 0; i4 < 16; ++i4) { if ((i4 & 3) == 0) asm volatile("" ::: "memory");
;             acc += hv[i4].x * wc4[4 * i4] + hv[i4].y * wc4[4 * i4 + 1] + hv[i4].z * wc4[4 * i4 + 2] + hv[i4].w * wc4[4 * i4 + 3]; }
	v_mul_f32_e32 v194, v48, v148
	v_mul_f32_e32 v195, v48, v149
	v_mul_f32_e32 v196, v48, v150
	v_mul_f32_e32 v197, v48, v151
	v_fmac_f32_e32 v194, v49, v154
	v_fmac_f32_e32 v195, v49, v155
	v_fmac_f32_e32 v196, v49, v156
	v_fmac_f32_e32 v197, v49, v157
	v_fmac_f32_e32 v194, v50, v158
	v_fmac_f32_e32 v195, v50, v159
	v_fmac_f32_e32 v196, v50, v160
	v_fmac_f32_e32 v197, v50, v161
	v_fmac_f32_e32 v194, v51, v162
	v_fmac_f32_e32 v195, v51, v163
	v_fmac_f32_e32 v196, v51, v164
	v_fmac_f32_e32 v197, v51, v165
	v_add_f32_dpp v194, v194, v194 row_ror:8 row_mask:0xf bank_mask:0xf
	v_add_f32_dpp v195, v195, v195 row_ror:8 row_mask:0xf bank_mask:0xf
	v_add_f32_dpp v196, v196, v196 row_ror:8 row_mask:0xf bank_mask:0xf
	v_add_f32_dpp v197, v197, v197 row_ror:8 row_mask:0xf bank_mask:0xf
	v_add_f32_dpp v194, v194, v194 row_ror:4 row_mask:0xf bank_mask:0xf
	v_add_f32_dpp v195, v195, v195 row_ror:4 row_mask:0xf bank_mask:0xf
	v_add_f32_dpp v196, v196, v196 row_ror:4 row_mask:0xf bank_mask:0xf
	v_add_f32_dpp v197, v197, v197 row_ror:4 row_mask:0xf bank_mask:0xf
	v_add_f32_dpp v194, v194, v194 row_ror:2 row_mask:0xf bank_mask:0xf
	v_add_f32_dpp v195, v195, v195 row_ror:2 row_mask:0xf bank_mask:0xf
	v_add_f32_dpp v196, v196, v196 row_ror:2 row_mask:0xf bank_mask:0xf
	v_add_f32_dpp v197, v197, v197 row_ror:2 row_mask:0xf bank_mask:0xf
	v_add_f32_dpp v194, v194, v194 row_ror:1 row_mask:0xf bank_mask:0xf
	v_add_f32_dpp v195, v195, v195 row_ror:1 row_mask:0xf bank_mask:0xf
	v_add_f32_dpp v196, v196, v196 row_ror:1 row_mask:0xf bank_mask:0xf
	v_add_f32_dpp v197, v197, v197 row_ror:1 row_mask:0xf bank_mask:0xf
	s_mov_b64 exec, s[2:3]
	ds_write_b128 v251, v[194:197] offset:768
	s_mov_b64 exec, -1
	global_load_dwordx4 v[48:51], v[200:201], off offset:0
	s_waitcnt vmcnt(15)
	v_mul_f32_e32 v210, v52, v148
	v_mul_f32_e32 v211, v52, v149
	v_mul_f32_e32 v212, v52, v150
	v_mul_f32_e32 v213, v52, v151
	v_fmac_f32_e32 v210, v53, v154
	v_fmac_f32_e32 v211, v53, v155
	v_fmac_f32_e32 v212, v53, v156
	v_fmac_f32_e32 v213, v53, v157
	v_fmac_f32_e32 v210, v54, v158
	v_fmac_f32_e32 v211, v54, v159
	v_fmac_f32_e32 v212, v54, v160
	v_fmac_f32_e32 v213, v54, v161
	v_fmac_f32_e32 v210, v55, v162
	v_fmac_f32_e32 v211, v55, v163
	v_fmac_f32_e32 v212, v55, v164
	v_fmac_f32_e32 v213, v55, v165
	v_add_f32_dpp v210, v210, v210 row_ror:8 row_mask:0xf bank_mask:0xf
	v_add_f32_dpp v211, v211, v211 row_ror:8 row_mask:0xf bank_mask:0xf
	v_add_f32_dpp v212, v212, v212 row_ror:8 row_mask:0xf bank_mask:0xf
	v_add_f32_dpp v213, v213, v213 row_ror:8 row_mask:0xf bank_mask:0xf
	v_add_f32_dpp v210, v210, v210 row_ror:4 row_mask:0xf bank_mask:0xf
	v_add_f32_dpp v211, v211, v211 row_ror:4 row_mask:0xf bank_mask:0xf
	v_add_f32_dpp v212, v212, v212 row_ror:4 row_mask:0xf bank_mask:0xf
	v_add_f32_dpp v213, v213, v213 row_ror:4 row_mask:0xf bank_mask:0xf
	v_add_f32_dpp v210, v210, v210 row_ror:2 row_mask:0xf bank_mask:0xf
	v_add_f32_dpp v211, v211, v211 row_ror:2 row_mask:0xf bank_mask:0xf
	v_add_f32_dpp v212, v212, v212 row_ror:2 row_mask:0xf bank_mask:0xf
	v_add_f32_dpp v213, v213, v213 row_ror:2 row_mask:0xf bank_mask:0xf
	v_add_f32_dpp v210, v210, v210 row_ror:1 row_mask:0xf bank_mask:0xf
	v_add_f32_dpp v211, v211, v211 row_ror:1 row_mask:0xf bank_mask:0xf
	v_add_f32_dpp v212, v212, v212 row_ror:1 row_mask:0xf bank_mask:0xf
	v_add_f32_dpp v213, v213, v213 row_ror:1 row_mask:0xf bank_mask:0xf
	s_mov_b64 exec, s[2:3]
	ds_write_b128 v251, v[210:213] offset:832
	s_mov_b64 exec, -1
	global_load_dwordx4 v[52:55], v[200:201], off offset:1024
	s_waitcnt vmcnt(15)
; template <int L, int N> DEVQ void filt_item(const Params& P, LAS unsigned char* lds, const float* H3v, int d, cf* specd, float* cornerd) {
;     ...
;     for (int k = tid; k < L; k += NTHR) {
;         asm volatile("" ::: "memory");
;         const f32x4* hr = (const f32x4*)(H3v + (size_t)k * 64);
;         f32x4 acc = (f32x4){0.f, 0.f, 0.f, 0.f};
;         f32x4 hv[16];
; #pragma unroll
;         for (int i4 = 0; i4 < 16; ++i4) hv[i4] = hr[i4];
; #pragma unroll
;         for (int i4 = 0; i4 < 16; ++i4) { if ((i4 & 3) == 0) asm volatile("" ::: "memory");
;             acc += hv[i4].x * wc4[4 * i4] + hv[i4].y * wc4[4 * i4 + 1] + hv[i4].z * wc4[4 * i4 + 2] + hv[i4].w * wc4[4 * i4 + 3]; }
;         const float dec = expf(-((float)k / (float)(L - 1)) * delta);
;         acc *= dec;
;         if (k <= N / 2) X[swz(k)] = cf{acc.x * invN, acc.z * invN};
	v_mul_f32_e32 v194, v56, v148
	v_mul_f32_e32 v195, v56, v149
	v_mul_f32_e32 v196, v56, v150
	v_mul_f32_e32 v197, v56, v151
	v_fmac_f32_e32 v194, v57, v154
	v_fmac_f32_e32 v195, v57, v155
	v_fmac_f32_e32 v196, v57, v156
	v_fmac_f32_e32 v197, v57, v157
	v_fmac_f32_e32 v194, v58, v158
	v_fmac_f32_e32 v195, v58, v159
	v_fmac_f32_e32 v196, v58, v160
	v_fmac_f32_e32 v197, v58, v161
	v_fmac_f32_e32 v194, v59, v162
	v_fmac_f32_e32 v195, v59, v163
	v_fmac_f32_e32 v196, v59, v164
	v_fmac_f32_e32 v197, v59, v165
	v_add_f32_dpp v194, v194, v194 row_ror:8 row_mask:0xf bank_mask:0xf
	v_add_f32_dpp v195, v195, v195 row_ror:8 row_mask:0xf bank_mask:0xf
	v_add_f32_dpp v196, v196, v196 row_ror:8 row_mask:0xf bank_mask:0xf
	v_add_f32_dpp v197, v197, v197 row_ror:8 row_mask:0xf bank_mask:0xf
	v_add_f32_dpp v194, v194, v194 row_ror:4 row_mask:0xf bank_mask:0xf
	v_add_f32_dpp v195, v195, v195 row_ror:4 row_mask:0xf bank_mask:0xf
	v_add_f32_dpp v196, v196, v196 row_ror:4 row_mask:0xf bank_mask:0xf
	v_add_f32_dpp v197, v197, v197 row_ror:4 row_mask:0xf bank_mask:0xf
	v_add_f32_dpp v194, v194, v194 row_ror:2 row_mask:0xf bank_mask:0xf
	v_add_f32_dpp v195, v195, v195 row_ror:2 row_mask:0xf bank_mask:0xf
	v_add_f32_dpp v196, v196, v196 row_ror:2 row_mask:0xf bank_mask:0xf
	v_add_f32_dpp v197, v197, v197 row_ror:2 row_mask:0xf bank_mask:0xf
	v_add_f32_dpp v194, v194, v194 row_ror:1 row_mask:0xf bank_mask:0xf
	v_add_f32_dpp v195, v195, v195 row_ror:1 row_mask:0xf bank_mask:0xf
	v_add_f32_dpp v196, v196, v196 row_ror:1 row_mask:0xf bank_mask:0xf
	v_add_f32_dpp v197, v197, v197 row_ror:1 row_mask:0xf bank_mask:0xf
	s_mov_b64 exec, s[2:3]
	ds_write_b128 v251, v[194:197] offset:896
	s_mov_b64 exec, -1
	global_load_dwordx4 v[56:59], v[200:201], off offset:2048
	s_waitcnt vmcnt(15)
	v_mul_f32_e32 v210, v60, v148
	v_mul_f32_e32 v211, v60, v149
	v_mul_f32_e32 v212, v60, v150
	v_mul_f32_e32 v213, v60, v151
	v_fmac_f32_e32 v210, v61, v154
	v_fmac_f32_e32 v211, v61, v155
	v_fmac_f32_e32 v212, v61, v156
	v_fmac_f32_e32 v213, v61, v157
	v_fmac_f32_e32 v210, v62, v158
	v_fmac_f32_e32 v211, v62, v159
	v_fmac_f32_e32 v212, v62, v160
	v_fmac_f32_e32 v213, v62, v161
	v_fmac_f32_e32 v210, v63, v162
	v_fmac_f32_e32 v211, v63, v163
	v_fmac_f32_e32 v212, v63, v164
	v_fmac_f32_e32 v213, v63, v165
	v_add_f32_dpp v210, v210, v210 row_ror:8 row_mask:0xf bank_mask:0xf
	v_add_f32_dpp v211, v211, v211 row_ror:8 row_mask:0xf bank_mask:0xf
	v_add_f32_dpp v212, v212, v212 row_ror:8 row_mask:0xf bank_mask:0xf
	v_add_f32_dpp v213, v213, v213 row_ror:8 row_mask:0xf bank_mask:0xf
	v_add_f32_dpp v210, v210, v210 row_ror:4 row_mask:0xf bank_mask:0xf
	v_add_f32_dpp v211, v211, v211 row_ror:4 row_mask:0xf bank_mask:0xf
	v_add_f32_dpp v212, v212, v212 row_ror:4 row_mask:0xf bank_mask:0xf
	v_add_f32_dpp v213, v213, v213 row_ror:4 row_mask:0xf bank_mask:0xf
	v_add_f32_dpp v210, v210, v210 row_ror:2 row_mask:0xf bank_mask:0xf
	v_add_f32_dpp v211, v211, v211 row_ror:2 row_mask:0xf bank_mask:0xf
	v_add_f32_dpp v212, v212, v212 row_ror:2 row_mask:0xf bank_mask:0xf
	v_add_f32_dpp v213, v213, v213 row_ror:2 row_mask:0xf bank_mask:0xf
	v_add_f32_dpp v210, v210, v210 row_ror:1 row_mask:0xf bank_mask:0xf
	v_add_f32_dpp v211, v211, v211 row_ror:1 row_mask:0xf bank_mask:0xf
	v_add_f32_dpp v212, v212, v212 row_ror:1 row_mask:0xf bank_mask:0xf
	v_add_f32_dpp v213, v213, v213 row_ror:1 row_mask:0xf bank_mask:0xf
	s_mov_b64 exec, s[2:3]
	ds_write_b128 v251, v[210:213] offset:960
	s_mov_b64 exec, -1
	global_load_dwordx4 v[60:63], v[200:201], off offset:3072
	s_waitcnt lgkmcnt(0)
	ds_read_b128 v[0:3], v250
	s_mov_b32 s11, 0xc5807800
	v_cvt_f32_i32_e32 v4, v75
	s_waitcnt lgkmcnt(0)
	s_mov_b64 exec, s[14:15]
	v_div_scale_f32 v5, s[2:3], s11, s11, v4
	v_rcp_f32_e32 v6, v5
	s_mov_b32 s2, 0xc2ce8ed0
	v_fma_f32 v7, -v5, v6, 1.0
	v_fmac_f32_e32 v6, v7, v6
	v_div_scale_f32 v7, vcc, v4, s11, v4
	v_mul_f32_e32 v8, v7, v6
	v_fma_f32 v9, -v5, v8, v7
	v_fmac_f32_e32 v8, v9, v6
	v_fma_f32 v5, -v5, v8, v7
	v_div_fmas_f32 v5, v5, v6, v8
	v_div_fixup_f32 v4, v5, s11, v4
	v_mul_f32_e64 v4, |v74|, v4
	v_mul_f32_e32 v5, 0x3fb8aa3b, v4
	v_fma_f32 v6, v4, s18, -v5
	v_rndne_f32_e32 v7, v5
	v_fmac_f32_e32 v6, 0x32a5705f, v4
	v_sub_f32_e32 v5, v5, v7
	v_add_f32_e32 v5, v5, v6
	v_exp_f32_e32 v5, v5
	v_cvt_i32_f32_e32 v6, v7
	v_cmp_ngt_f32_e32 vcc, s2, v4
	s_mov_b32 s2, 0x42b17218
	v_ldexp_f32 v5, v5, v6
	v_cndmask_b32_e32 v5, 0, v5, vcc
	v_cmp_nlt_f32_e32 vcc, s2, v4
	s_movk_i32 s2, 0x1001
	s_nop 0
	v_cndmask_b32_e32 v4, v188, v5, vcc
	v_pk_mul_f32 v[0:1], v[4:5], v[0:1] op_sel_hi:[0,1]
	v_pk_mul_f32 v[2:3], v[4:5], v[2:3] op_sel_hi:[0,1]
	v_cmp_gt_i32_e32 vcc, s2, v75
	s_and_saveexec_b64 s[14:15], vcc
	s_cbranch_execz .LBB0_593
	v_ashrrev_i32_e32 v6, 5, v75
	v_lshlrev_b32_e32 v7, 2, v6
	v_and_b32_e32 v7, 28, v7
	v_and_b32_e32 v6, 3, v6
	v_mov_b32_e32 v4, v0
	v_mov_b32_e32 v5, v2
	s_mov_b32 s2, 0x39000000
	v_bitop3_b32 v6, v7, v75, v6 bitop3:0x36
	v_pk_mul_f32 v[4:5], v[4:5], s[2:3] op_sel_hi:[1,0]
	v_lshl_add_u32 v6, v6, 3, 0
	ds_write_b64 v6, v[4:5]

; #define LAS __attribute__((address_space(3)))
; template <int L, int N> DEVQ void filt_item(const Params& P, LAS unsigned char* lds, const float* H3v, int d, cf* specd, float* cornerd) {
;     ...
;     __syncthreads();
;     if (tid < 64) { const int o = tid >> 5, kk = tid & 31; float v = 0.f;
;         const LAS float* hf = edge + 64 * o; const LAS float* hb = hf + 32;
;         if (kk < 15) v = hf[16 + kk] - hb[14 - kk];
;         else if (kk >= 16) { const int q = kk - 16; v = hb[15 + q] - hf[15 - q]; }
;         cornerd[tid] = v; }
.LBB0_597:
	s_waitcnt vmcnt(0)
	s_or_b64 exec, exec, s[0:1]
	s_waitcnt lgkmcnt(0)
	s_barrier
	s_and_saveexec_b64 s[0:1], s[4:5]
	s_cbranch_execz .LBB0_605
	s_waitcnt vmcnt(0)
	v_lshlrev_b32_e32 v0, 3, v64
	v_and_b32_e32 v1, 31, v64
	v_and_b32_e32 v0, 0xffffff00, v0
	v_readlane_b32 s2, v254, 31
	v_cmp_lt_u32_e32 vcc, 14, v1
	s_nop 0
	v_add_u32_e32 v2, s2, v0
	s_and_saveexec_b64 s[2:3], vcc
	s_xor_b64 s[4:5], exec, s[2:3]
	s_cbranch_execz .LBB0_602
	v_cmp_ne_u32_e32 vcc, 15, v1
	v_mov_b32_e32 v0, 0
	s_and_saveexec_b64 s[12:13], vcc
	s_cbranch_execz .LBB0_601
	v_lshl_add_u32 v0, v1, 2, v2
	v_xor_b32_e32 v1, 31, v1
	v_lshl_add_u32 v1, v1, 2, v2
	ds_read_b32 v0, v0 offset:124
	ds_read_b32 v1, v1
	s_waitcnt lgkmcnt(0)
	v_sub_f32_e32 v0, v0, v1

; template <int L, int N> DEVQ void filt_item(const Params& P, LAS unsigned char* lds, const float* H3v, int d, cf* specd, float* cornerd) {
;     ...
;     const float delta = fabsf(MIN_DECAY + (float)d * ((MAX_DECAY - MIN_DECAY) / 1023.0f));
;     const float invN = 1.0f / (float)N;
;     for (int k = tid; k < L; k += NTHR) {
;         asm volatile("" ::: "memory");
;         const f32x4* hr = (const f32x4*)(H3v + (size_t)k * 64);
;         f32x4 acc = (f32x4){0.f, 0.f, 0.f, 0.f};
;         f32x4 hv[16];
; #pragma unroll
;         for (int i4 = 0; i4 < 16; ++i4) hv[i4] = hr[i4];
; #pragma unroll
;         for (int i4 = 0; i4 < 16; ++i4) { if ((i4 & 3) == 0) asm volatile("" ::: "memory");
;             acc += hv[i4].x * wc4[4 * i4] + hv[i4].y * wc4[4 * i4 + 1] + hv[i4].z * wc4[4 * i4 + 2] + hv[i4].w * wc4[4 * i4 + 3]; }
.LBB0_624:
	s_or_b64 exec, exec, s[0:1]
	s_movk_i32 s0, 0x2010
	v_cmp_gt_i32_e32 vcc, s0, v64
	s_waitcnt lgkmcnt(0)
	s_barrier
	s_and_saveexec_b64 s[0:1], vcc
	s_cbranch_execz .LBB0_633
	s_waitcnt vmcnt(0)
	v_cvt_f32_i32_e32 v2, s12
	v_readlane_b32 s2, v254, 32
	v_lshlrev_b64 v[0:1], 8, v[64:65]
	v_mov_b32_e32 v3, 0xc0447cbd
	v_lshl_add_u32 v72, v64, 2, s2
	v_sub_u32_e32 v73, 0x4000, v64
	v_fmamk_f32 v74, v2, 0xbc44ade8, v3
	v_lshl_add_u64 v[66:67], s[6:7], 0, v[0:1]
	s_mov_b64 s[14:15], 0
	v_mov_b32_e32 v75, v64
	v_mbcnt_lo_u32_b32 v202, -1, 0
	v_mbcnt_hi_u32_b32 v202, -1, v202
	v_mul_u32_u24_e32 v203, 0xf0, v202
	v_sub_u32_e32 v248, 0x1000, v203
	v_sub_u32_e32 v246, 0x3000, v203
	v_ashrrev_i32_e32 v249, 31, v248
	v_ashrrev_i32_e32 v247, 31, v246
	v_and_b32_e32 v203, 15, v202
	v_lshl_add_u32 v203, v203, 6, 0
	v_add_u32_e32 v203, 0x20000, v203
	ds_read_b128 v[148:151], v203
	ds_read_b128 v[154:157], v203 offset:16
	ds_read_b128 v[158:161], v203 offset:32
	ds_read_b128 v[162:165], v203 offset:48
	v_lshrrev_b32_e32 v204, 6, v64
	v_cmp_lt_u32_e64 s[2:3], 5, v204
	v_lshl_add_u32 v204, v204, 10, 0
	v_mov_b32_e32 v205, 0x400
	v_add_u32_e32 v204, 0x20800, v204
	v_cndmask_b32_e64 v205, 0, v205, s[2:3]
	v_add_u32_e32 v204, v204, v205
	v_lshrrev_b32_e32 v205, 4, v202
	v_lshl_add_u32 v251, v205, 4, v204
	v_lshl_add_u32 v250, v202, 4, v204
	v_add_co_u32_e32 v226, vcc, 0x20000, v248
	s_nop 1
	v_addc_co_u32_e32 v227, vcc, 0, v249, vcc
	v_add_co_u32_e32 v228, vcc, 0x20000, v246
	s_nop 1
	v_addc_co_u32_e32 v229, vcc, 0, v247, vcc
	v_lshl_add_u64 v[198:199], v[66:67], 0, v[248:249]
	v_lshl_add_u64 v[200:201], v[66:67], 0, v[246:247]
	global_load_dwordx4 v[214:217], v[198:199], off offset:-4096
	global_load_dwordx4 v[218:221], v[198:199], off offset:-3072
	global_load_dwordx4 v[222:225], v[198:199], off offset:-2048
	global_load_dwordx4 v[12:15], v[198:199], off offset:-1024
	global_load_dwordx4 v[16:19], v[198:199], off offset:0
	global_load_dwordx4 v[20:23], v[198:199], off offset:1024
	global_load_dwordx4 v[24:27], v[198:199], off offset:2048
	global_load_dwordx4 v[28:31], v[198:199], off offset:3072
	global_load_dwordx4 v[32:35], v[200:201], off offset:-4096
	global_load_dwordx4 v[36:39], v[200:201], off offset:-3072
	global_load_dwordx4 v[40:43], v[200:201], off offset:-2048
	global_load_dwordx4 v[44:47], v[200:201], off offset:-1024
	global_load_dwordx4 v[48:51], v[200:201], off offset:0
	global_load_dwordx4 v[52:55], v[200:201], off offset:1024
	global_load_dwordx4 v[56:59], v[200:201], off offset:2048
	global_load_dwordx4 v[60:63], v[200:201], off offset:3072
	s_waitcnt lgkmcnt(0)
	s_branch .LBB0_627

; template <int L, int N> DEVQ void filt_item(const Params& P, LAS unsigned char* lds, const float* H3v, int d, cf* specd, float* cornerd) {
;     ...
;     for (int k = tid; k < L; k += NTHR) {
;         asm volatile("" ::: "memory");
;         const f32x4* hr = (const f32x4*)(H3v + (size_t)k * 64);
;         f32x4 acc = (f32x4){0.f, 0.f, 0.f, 0.f};
;         f32x4 hv[16];
; #pragma unroll
;         for (int i4 = 0; i4 < 16; ++i4) hv[i4] = hr[i4];
; #pragma unroll
;         for (int i4 = 0; i4 < 16; ++i4) { if ((i4 & 3) == 0) asm volatile("" ::: "memory");
;             acc += hv[i4].x * wc4[4 * i4] + hv[i4].y * wc4[4 * i4 + 1] + hv[i4].z * wc4[4 * i4 + 2] + hv[i4].w * wc4[4 * i4 + 3]; }
.LBB0_627:
	s_mov_b64 s[20:21], exec
	s_mov_b64 exec, -1
	v_lshl_add_u64 v[198:199], v[66:67], 0, v[226:227]
	v_lshl_add_u64 v[200:201], v[66:67], 0, v[228:229]
	s_mov_b32 s2, 0x10001
	s_mov_b32 s3, 0x10001
	s_waitcnt vmcnt(15)
	v_mul_f32_e32 v194, v214, v148
	v_mul_f32_e32 v195, v214, v149
	v_mul_f32_e32 v196, v214, v150
	v_mul_f32_e32 v197, v214, v151
	v_fmac_f32_e32 v194, v215, v154
	v_fmac_f32_e32 v195, v215, v155
	v_fmac_f32_e32 v196, v215, v156
	v_fmac_f32_e32 v197, v215, v157
	v_fmac_f32_e32 v194, v216, v158
	v_fmac_f32_e32 v195, v216, v159
	v_fmac_f32_e32 v196, v216, v160
	v_fmac_f32_e32 v197, v216, v161
	v_fmac_f32_e32 v194, v217, v162
	v_fmac_f32_e32 v195, v217, v163
	v_fmac_f32_e32 v196, v217, v164
	v_fmac_f32_e32 v197, v217, v165
	v_add_f32_dpp v194, v194, v194 row_ror:8 row_mask:0xf bank_mask:0xf
	v_add_f32_dpp v195, v195, v195 row_ror:8 row_mask:0xf bank_mask:0xf
	v_add_f32_dpp v196, v196, v196 row_ror:8 row_mask:0xf bank_mask:0xf
	v_add_f32_dpp v197, v197, v197 row_ror:8 row_mask:0xf bank_mask:0xf
	v_add_f32_dpp v194, v194, v194 row_ror:4 row_mask:0xf bank_mask:0xf
	v_add_f32_dpp v195, v195, v195 row_ror:4 row_mask:0xf bank_mask:0xf
	v_add_f32_dpp v196, v196, v196 row_ror:4 row_mask:0xf bank_mask:0xf
	v_add_f32_dpp v197, v197, v197 row_ror:4 row_mask:0xf bank_mask:0xf
	v_add_f32_dpp v194, v194, v194 row_ror:2 row_mask:0xf bank_mask:0xf
	v_add_f32_dpp v195, v195, v195 row_ror:2 row_mask:0xf bank_mask:0xf
	v_add_f32_dpp v196, v196, v196 row_ror:2 row_mask:0xf bank_mask:0xf
	v_add_f32_dpp v197, v197, v197 row_ror:2 row_mask:0xf bank_mask:0xf
	v_add_f32_dpp v194, v194, v194 row_ror:1 row_mask:0xf bank_mask:0xf
	v_add_f32_dpp v195, v195, v195 row_ror:1 row_mask:0xf bank_mask:0xf
	v_add_f32_dpp v196, v196, v196 row_ror:1 row_mask:0xf bank_mask:0xf
	v_add_f32_dpp v197, v197, v197 row_ror:1 row_mask:0xf bank_mask:0xf
	s_mov_b64 exec, s[2:3]
	ds_write_b128 v251, v[194:197]
	s_mov_b64 exec, -1
	global_load_dwordx4 v[214:217], v[198:199], off offset:-4096
	s_waitcnt vmcnt(15)
	v_mul_f32_e32 v210, v218, v148
	v_mul_f32_e32 v211, v218, v149
	v_mul_f32_e32 v212, v218, v150
	v_mul_f32_e32 v213, v218, v151
	v_fmac_f32_e32 v210, v219, v154
	v_fmac_f32_e32 v211, v219, v155
	v_fmac_f32_e32 v212, v219, v156
	v_fmac_f32_e32 v213, v219, v157
	v_fmac_f32_e32 v210, v220, v158
	v_fmac_f32_e32 v211, v220, v159
	v_fmac_f32_e32 v212, v220, v160
	v_fmac_f32_e32 v213, v220, v161
	v_fmac_f32_e32 v210, v221, v162
	v_fmac_f32_e32 v211, v221, v163
	v_fmac_f32_e32 v212, v221, v164
	v_fmac_f32_e32 v213, v221, v165
	v_add_f32_dpp v210, v210, v210 row_ror:8 row_mask:0xf bank_mask:0xf
	v_add_f32_dpp v211, v211, v211 row_ror:8 row_mask:0xf bank_mask:0xf
	v_add_f32_dpp v212, v212, v212 row_ror:8 row_mask:0xf bank_mask:0xf
	v_add_f32_dpp v213, v213, v213 row_ror:8 row_mask:0xf bank_mask:0xf
	v_add_f32_dpp v210, v210, v210 row_ror:4 row_mask:0xf bank_mask:0xf
	v_add_f32_dpp v211, v211, v211 row_ror:4 row_mask:0xf bank_mask:0xf
	v_add_f32_dpp v212, v212, v212 row_ror:4 row_mask:0xf bank_mask:0xf
	v_add_f32_dpp v213, v213, v213 row_ror:4 row_mask:0xf bank_mask:0xf
	v_add_f32_dpp v210, v210, v210 row_ror:2 row_mask:0xf bank_mask:0xf
	v_add_f32_dpp v211, v211, v211 row_ror:2 row_mask:0xf bank_mask:0xf
	v_add_f32_dpp v212, v212, v212 row_ror:2 row_mask:0xf bank_mask:0xf
	v_add_f32_dpp v213, v213, v213 row_ror:2 row_mask:0xf bank_mask:0xf
	v_add_f32_dpp v210, v210, v210 row_ror:1 row_mask:0xf bank_mask:0xf
	v_add_f32_dpp v211, v211, v211 row_ror:1 row_mask:0xf bank_mask:0xf
	v_add_f32_dpp v212, v212, v212 row_ror:1 row_mask:0xf bank_mask:0xf
	v_add_f32_dpp v213, v213, v213 row_ror:1 row_mask:0xf bank_mask:0xf
	s_mov_b64 exec, s[2:3]
	ds_write_b128 v251, v[210:213] offset:64
	s_mov_b64 exec, -1
	global_load_dwordx4 v[218:221], v[198:199], off offset:-3072
	s_waitcnt vmcnt(15)
	v_mul_f32_e32 v194, v222, v148
	v_mul_f32_e32 v195, v222, v149
	v_mul_f32_e32 v196, v222, v150
	v_mul_f32_e32 v197, v222, v151
	v_fmac_f32_e32 v194, v223, v154
	v_fmac_f32_e32 v195, v223, v155
	v_fmac_f32_e32 v196, v223, v156
	v_fmac_f32_e32 v197, v223, v157
	v_fmac_f32_e32 v194, v224, v158
	v_fmac_f32_e32 v195, v224, v159
	v_fmac_f32_e32 v196, v224, v160
	v_fmac_f32_e32 v197, v224, v161
	v_fmac_f32_e32 v194, v225, v162
	v_fmac_f32_e32 v195, v225, v163
	v_fmac_f32_e32 v196, v225, v164
	v_fmac_f32_e32 v197, v225, v165
	v_add_f32_dpp v194, v194, v194 row_ror:8 row_mask:0xf bank_mask:0xf
	v_add_f32_dpp v195, v195, v195 row_ror:8 row_mask:0xf bank_mask:0xf
	v_add_f32_dpp v196, v196, v196 row_ror:8 row_mask:0xf bank_mask:0xf
	v_add_f32_dpp v197, v197, v197 row_ror:8 row_mask:0xf bank_mask:0xf
	v_add_f32_dpp v194, v194, v194 row_ror:4 row_mask:0xf bank_mask:0xf
	v_add_f32_dpp v195, v195, v195 row_ror:4 row_mask:0xf bank_mask:0xf
	v_add_f32_dpp v196, v196, v196 row_ror:4 row_mask:0xf bank_mask:0xf
	v_add_f32_dpp v197, v197, v197 row_ror:4 row_mask:0xf bank_mask:0xf
	v_add_f32_dpp v194, v194, v194 row_ror:2 row_mask:0xf bank_mask:0xf
	v_add_f32_dpp v195, v195, v195 row_ror:2 row_mask:0xf bank_mask:0xf
	v_add_f32_dpp v196, v196, v196 row_ror:2 row_mask:0xf bank_mask:0xf
	v_add_f32_dpp v197, v197, v197 row_ror:2 row_mask:0xf bank_mask:0xf
	v_add_f32_dpp v194, v194, v194 row_ror:1 row_mask:0xf bank_mask:0xf
	v_add_f32_dpp v195, v195, v195 row_ror:1 row_mask:0xf bank_mask:0xf
	v_add_f32_dpp v196, v196, v196 row_ror:1 row_mask:0xf bank_mask:0xf
	v_add_f32_dpp v197, v197, v197 row_ror:1 row_mask:0xf bank_mask:0xf
	s_mov_b64 exec, s[2:3]
	ds_write_b128 v251, v[194:197] offset:128
	s_mov_b64 exec, -1
	global_load_dwordx4 v[222:225], v[198:199], off offset:-2048
	s_waitcnt vmcnt(15)
; template <int L, int N> DEVQ void filt_item(const Params& P, LAS unsigned char* lds, const float* H3v, int d, cf* specd, float* cornerd) {
;     ...
;     for (int k = tid; k < L; k += NTHR) {
;         asm volatile("" ::: "memory");
;         const f32x4* hr = (const f32x4*)(H3v + (size_t)k * 64);
;         f32x4 acc = (f32x4){0.f, 0.f, 0.f, 0.f};
;         f32x4 hv[16];
; #pragma unroll
;         for (int i4 = 0; i4 < 16; ++i4) hv[i4] = hr[i4];
; #pragma unroll
;         for (int i4 = 0; i4 < 16; ++i4) { if ((i4 & 3) == 0) asm volatile("" ::: "memory");
;             acc += hv[i4].x * wc4[4 * i4] + hv[i4].y * wc4[4 * i4 + 1] + hv[i4].z * wc4[4 * i4 + 2] + hv[i4].w * wc4[4 * i4 + 3]; }
	v_mul_f32_e32 v210, v12, v148
	v_mul_f32_e32 v211, v12, v149
	v_mul_f32_e32 v212, v12, v150
	v_mul_f32_e32 v213, v12, v151
	v_fmac_f32_e32 v210, v13, v154
	v_fmac_f32_e32 v211, v13, v155
	v_fmac_f32_e32 v212, v13, v156
	v_fmac_f32_e32 v213, v13, v157
	v_fmac_f32_e32 v210, v14, v158
	v_fmac_f32_e32 v211, v14, v159
	v_fmac_f32_e32 v212, v14, v160
	v_fmac_f32_e32 v213, v14, v161
	v_fmac_f32_e32 v210, v15, v162
	v_fmac_f32_e32 v211, v15, v163
	v_fmac_f32_e32 v212, v15, v164
	v_fmac_f32_e32 v213, v15, v165
	v_add_f32_dpp v210, v210, v210 row_ror:8 row_mask:0xf bank_mask:0xf
	v_add_f32_dpp v211, v211, v211 row_ror:8 row_mask:0xf bank_mask:0xf
	v_add_f32_dpp v212, v212, v212 row_ror:8 row_mask:0xf bank_mask:0xf
	v_add_f32_dpp v213, v213, v213 row_ror:8 row_mask:0xf bank_mask:0xf
	v_add_f32_dpp v210, v210, v210 row_ror:4 row_mask:0xf bank_mask:0xf
	v_add_f32_dpp v211, v211, v211 row_ror:4 row_mask:0xf bank_mask:0xf
	v_add_f32_dpp v212, v212, v212 row_ror:4 row_mask:0xf bank_mask:0xf
	v_add_f32_dpp v213, v213, v213 row_ror:4 row_mask:0xf bank_mask:0xf
	v_add_f32_dpp v210, v210, v210 row_ror:2 row_mask:0xf bank_mask:0xf
	v_add_f32_dpp v211, v211, v211 row_ror:2 row_mask:0xf bank_mask:0xf
	v_add_f32_dpp v212, v212, v212 row_ror:2 row_mask:0xf bank_mask:0xf
	v_add_f32_dpp v213, v213, v213 row_ror:2 row_mask:0xf bank_mask:0xf
	v_add_f32_dpp v210, v210, v210 row_ror:1 row_mask:0xf bank_mask:0xf
	v_add_f32_dpp v211, v211, v211 row_ror:1 row_mask:0xf bank_mask:0xf
	v_add_f32_dpp v212, v212, v212 row_ror:1 row_mask:0xf bank_mask:0xf
	v_add_f32_dpp v213, v213, v213 row_ror:1 row_mask:0xf bank_mask:0xf
	s_mov_b64 exec, s[2:3]
	ds_write_b128 v251, v[210:213] offset:192
	s_mov_b64 exec, -1
	global_load_dwordx4 v[12:15], v[198:199], off offset:-1024
	s_waitcnt vmcnt(15)
	v_mul_f32_e32 v194, v16, v148
	v_mul_f32_e32 v195, v16, v149
	v_mul_f32_e32 v196, v16, v150
	v_mul_f32_e32 v197, v16, v151
	v_fmac_f32_e32 v194, v17, v154
	v_fmac_f32_e32 v195, v17, v155
	v_fmac_f32_e32 v196, v17, v156
	v_fmac_f32_e32 v197, v17, v157
	v_fmac_f32_e32 v194, v18, v158
	v_fmac_f32_e32 v195, v18, v159
	v_fmac_f32_e32 v196, v18, v160
	v_fmac_f32_e32 v197, v18, v161
	v_fmac_f32_e32 v194, v19, v162
	v_fmac_f32_e32 v195, v19, v163
	v_fmac_f32_e32 v196, v19, v164
	v_fmac_f32_e32 v197, v19, v165
	v_add_f32_dpp v194, v194, v194 row_ror:8 row_mask:0xf bank_mask:0xf
	v_add_f32_dpp v195, v195, v195 row_ror:8 row_mask:0xf bank_mask:0xf
	v_add_f32_dpp v196, v196, v196 row_ror:8 row_mask:0xf bank_mask:0xf
	v_add_f32_dpp v197, v197, v197 row_ror:8 row_mask:0xf bank_mask:0xf
	v_add_f32_dpp v194, v194, v194 row_ror:4 row_mask:0xf bank_mask:0xf
	v_add_f32_dpp v195, v195, v195 row_ror:4 row_mask:0xf bank_mask:0xf
	v_add_f32_dpp v196, v196, v196 row_ror:4 row_mask:0xf bank_mask:0xf
	v_add_f32_dpp v197, v197, v197 row_ror:4 row_mask:0xf bank_mask:0xf
	v_add_f32_dpp v194, v194, v194 row_ror:2 row_mask:0xf bank_mask:0xf
	v_add_f32_dpp v195, v195, v195 row_ror:2 row_mask:0xf bank_mask:0xf
	v_add_f32_dpp v196, v196, v196 row_ror:2 row_mask:0xf bank_mask:0xf
	v_add_f32_dpp v197, v197, v197 row_ror:2 row_mask:0xf bank_mask:0xf
	v_add_f32_dpp v194, v194, v194 row_ror:1 row_mask:0xf bank_mask:0xf
	v_add_f32_dpp v195, v195, v195 row_ror:1 row_mask:0xf bank_mask:0xf
	v_add_f32_dpp v196, v196, v196 row_ror:1 row_mask:0xf bank_mask:0xf
	v_add_f32_dpp v197, v197, v197 row_ror:1 row_mask:0xf bank_mask:0xf
	s_mov_b64 exec, s[2:3]
	ds_write_b128 v251, v[194:197] offset:256
	s_mov_b64 exec, -1
	global_load_dwordx4 v[16:19], v[198:199], off offset:0
	s_waitcnt vmcnt(15)
	v_mul_f32_e32 v210, v20, v148
	v_mul_f32_e32 v211, v20, v149
	v_mul_f32_e32 v212, v20, v150
	v_mul_f32_e32 v213, v20, v151
	v_fmac_f32_e32 v210, v21, v154
	v_fmac_f32_e32 v211, v21, v155
	v_fmac_f32_e32 v212, v21, v156
	v_fmac_f32_e32 v213, v21, v157
	v_fmac_f32_e32 v210, v22, v158
	v_fmac_f32_e32 v211, v22, v159
	v_fmac_f32_e32 v212, v22, v160
	v_fmac_f32_e32 v213, v22, v161
	v_fmac_f32_e32 v210, v23, v162
	v_fmac_f32_e32 v211, v23, v163
	v_fmac_f32_e32 v212, v23, v164
	v_fmac_f32_e32 v213, v23, v165
	v_add_f32_dpp v210, v210, v210 row_ror:8 row_mask:0xf bank_mask:0xf
	v_add_f32_dpp v211, v211, v211 row_ror:8 row_mask:0xf bank_mask:0xf
	v_add_f32_dpp v212, v212, v212 row_ror:8 row_mask:0xf bank_mask:0xf
	v_add_f32_dpp v213, v213, v213 row_ror:8 row_mask:0xf bank_mask:0xf
	v_add_f32_dpp v210, v210, v210 row_ror:4 row_mask:0xf bank_mask:0xf
	v_add_f32_dpp v211, v211, v211 row_ror:4 row_mask:0xf bank_mask:0xf
	v_add_f32_dpp v212, v212, v212 row_ror:4 row_mask:0xf bank_mask:0xf
	v_add_f32_dpp v213, v213, v213 row_ror:4 row_mask:0xf bank_mask:0xf
	v_add_f32_dpp v210, v210, v210 row_ror:2 row_mask:0xf bank_mask:0xf
	v_add_f32_dpp v211, v211, v211 row_ror:2 row_mask:0xf bank_mask:0xf
	v_add_f32_dpp v212, v212, v212 row_ror:2 row_mask:0xf bank_mask:0xf
	v_add_f32_dpp v213, v213, v213 row_ror:2 row_mask:0xf bank_mask:0xf
	v_add_f32_dpp v210, v210, v210 row_ror:1 row_mask:0xf bank_mask:0xf
	v_add_f32_dpp v211, v211, v211 row_ror:1 row_mask:0xf bank_mask:0xf
	v_add_f32_dpp v212, v212, v212 row_ror:1 row_mask:0xf bank_mask:0xf
	v_add_f32_dpp v213, v213, v213 row_ror:1 row_mask:0xf bank_mask:0xf
	s_mov_b64 exec, s[2:3]
	ds_write_b128 v251, v[210:213] offset:320
	s_mov_b64 exec, -1
	global_load_dwordx4 v[20:23], v[198:199], off offset:1024
	s_waitcnt vmcnt(15)
; template <int L, int N> DEVQ void filt_item(const Params& P, LAS unsigned char* lds, const float* H3v, int d, cf* specd, float* cornerd) {
;     ...
;     for (int k = tid; k < L; k += NTHR) {
;         asm volatile("" ::: "memory");
;         const f32x4* hr = (const f32x4*)(H3v + (size_t)k * 64);
;         f32x4 acc = (f32x4){0.f, 0.f, 0.f, 0.f};
;         f32x4 hv[16];
; #pragma unroll
;         for (int i4 = 0; i4 < 16; ++i4) hv[i4] = hr[i4];
; #pragma unroll
;         for (int i4 = 0; i4 < 16; ++i4) { if ((i4 & 3) == 0) asm volatile("" ::: "memory");
;             acc += hv[i4].x * wc4[4 * i4] + hv[i4].y * wc4[4 * i4 + 1] + hv[i4].z * wc4[4 * i4 + 2] + hv[i4].w * wc4[4 * i4 + 3]; }
	v_mul_f32_e32 v194, v24, v148
	v_mul_f32_e32 v195, v24, v149
	v_mul_f32_e32 v196, v24, v150
	v_mul_f32_e32 v197, v24, v151
	v_fmac_f32_e32 v194, v25, v154
	v_fmac_f32_e32 v195, v25, v155
	v_fmac_f32_e32 v196, v25, v156
	v_fmac_f32_e32 v197, v25, v157
	v_fmac_f32_e32 v194, v26, v158
	v_fmac_f32_e32 v195, v26, v159
	v_fmac_f32_e32 v196, v26, v160
	v_fmac_f32_e32 v197, v26, v161
	v_fmac_f32_e32 v194, v27, v162
	v_fmac_f32_e32 v195, v27, v163
	v_fmac_f32_e32 v196, v27, v164
	v_fmac_f32_e32 v197, v27, v165
	v_add_f32_dpp v194, v194, v194 row_ror:8 row_mask:0xf bank_mask:0xf
	v_add_f32_dpp v195, v195, v195 row_ror:8 row_mask:0xf bank_mask:0xf
	v_add_f32_dpp v196, v196, v196 row_ror:8 row_mask:0xf bank_mask:0xf
	v_add_f32_dpp v197, v197, v197 row_ror:8 row_mask:0xf bank_mask:0xf
	v_add_f32_dpp v194, v194, v194 row_ror:4 row_mask:0xf bank_mask:0xf
	v_add_f32_dpp v195, v195, v195 row_ror:4 row_mask:0xf bank_mask:0xf
	v_add_f32_dpp v196, v196, v196 row_ror:4 row_mask:0xf bank_mask:0xf
	v_add_f32_dpp v197, v197, v197 row_ror:4 row_mask:0xf bank_mask:0xf
	v_add_f32_dpp v194, v194, v194 row_ror:2 row_mask:0xf bank_mask:0xf
	v_add_f32_dpp v195, v195, v195 row_ror:2 row_mask:0xf bank_mask:0xf
	v_add_f32_dpp v196, v196, v196 row_ror:2 row_mask:0xf bank_mask:0xf
	v_add_f32_dpp v197, v197, v197 row_ror:2 row_mask:0xf bank_mask:0xf
	v_add_f32_dpp v194, v194, v194 row_ror:1 row_mask:0xf bank_mask:0xf
	v_add_f32_dpp v195, v195, v195 row_ror:1 row_mask:0xf bank_mask:0xf
	v_add_f32_dpp v196, v196, v196 row_ror:1 row_mask:0xf bank_mask:0xf
	v_add_f32_dpp v197, v197, v197 row_ror:1 row_mask:0xf bank_mask:0xf
	s_mov_b64 exec, s[2:3]
	ds_write_b128 v251, v[194:197] offset:384
	s_mov_b64 exec, -1
	global_load_dwordx4 v[24:27], v[198:199], off offset:2048
	s_waitcnt vmcnt(15)
	v_mul_f32_e32 v210, v28, v148
	v_mul_f32_e32 v211, v28, v149
	v_mul_f32_e32 v212, v28, v150
	v_mul_f32_e32 v213, v28, v151
	v_fmac_f32_e32 v210, v29, v154
	v_fmac_f32_e32 v211, v29, v155
	v_fmac_f32_e32 v212, v29, v156
	v_fmac_f32_e32 v213, v29, v157
	v_fmac_f32_e32 v210, v30, v158
	v_fmac_f32_e32 v211, v30, v159
	v_fmac_f32_e32 v212, v30, v160
	v_fmac_f32_e32 v213, v30, v161
	v_fmac_f32_e32 v210, v31, v162
	v_fmac_f32_e32 v211, v31, v163
	v_fmac_f32_e32 v212, v31, v164
	v_fmac_f32_e32 v213, v31, v165
	v_add_f32_dpp v210, v210, v210 row_ror:8 row_mask:0xf bank_mask:0xf
	v_add_f32_dpp v211, v211, v211 row_ror:8 row_mask:0xf bank_mask:0xf
	v_add_f32_dpp v212, v212, v212 row_ror:8 row_mask:0xf bank_mask:0xf
	v_add_f32_dpp v213, v213, v213 row_ror:8 row_mask:0xf bank_mask:0xf
	v_add_f32_dpp v210, v210, v210 row_ror:4 row_mask:0xf bank_mask:0xf
	v_add_f32_dpp v211, v211, v211 row_ror:4 row_mask:0xf bank_mask:0xf
	v_add_f32_dpp v212, v212, v212 row_ror:4 row_mask:0xf bank_mask:0xf
	v_add_f32_dpp v213, v213, v213 row_ror:4 row_mask:0xf bank_mask:0xf
	v_add_f32_dpp v210, v210, v210 row_ror:2 row_mask:0xf bank_mask:0xf
	v_add_f32_dpp v211, v211, v211 row_ror:2 row_mask:0xf bank_mask:0xf
	v_add_f32_dpp v212, v212, v212 row_ror:2 row_mask:0xf bank_mask:0xf
	v_add_f32_dpp v213, v213, v213 row_ror:2 row_mask:0xf bank_mask:0xf
	v_add_f32_dpp v210, v210, v210 row_ror:1 row_mask:0xf bank_mask:0xf
	v_add_f32_dpp v211, v211, v211 row_ror:1 row_mask:0xf bank_mask:0xf
	v_add_f32_dpp v212, v212, v212 row_ror:1 row_mask:0xf bank_mask:0xf
	v_add_f32_dpp v213, v213, v213 row_ror:1 row_mask:0xf bank_mask:0xf
	s_mov_b64 exec, s[2:3]
	ds_write_b128 v251, v[210:213] offset:448
	s_mov_b64 exec, -1
	global_load_dwordx4 v[28:31], v[198:199], off offset:3072
	s_waitcnt vmcnt(15)
	v_mul_f32_e32 v194, v32, v148
	v_mul_f32_e32 v195, v32, v149
	v_mul_f32_e32 v196, v32, v150
	v_mul_f32_e32 v197, v32, v151
	v_fmac_f32_e32 v194, v33, v154
	v_fmac_f32_e32 v195, v33, v155
	v_fmac_f32_e32 v196, v33, v156
	v_fmac_f32_e32 v197, v33, v157
	v_fmac_f32_e32 v194, v34, v158
	v_fmac_f32_e32 v195, v34, v159
	v_fmac_f32_e32 v196, v34, v160
	v_fmac_f32_e32 v197, v34, v161
	v_fmac_f32_e32 v194, v35, v162
	v_fmac_f32_e32 v195, v35, v163
	v_fmac_f32_e32 v196, v35, v164
	v_fmac_f32_e32 v197, v35, v165
	v_add_f32_dpp v194, v194, v194 row_ror:8 row_mask:0xf bank_mask:0xf
	v_add_f32_dpp v195, v195, v195 row_ror:8 row_mask:0xf bank_mask:0xf
	v_add_f32_dpp v196, v196, v196 row_ror:8 row_mask:0xf bank_mask:0xf
	v_add_f32_dpp v197, v197, v197 row_ror:8 row_mask:0xf bank_mask:0xf
	v_add_f32_dpp v194, v194, v194 row_ror:4 row_mask:0xf bank_mask:0xf
	v_add_f32_dpp v195, v195, v195 row_ror:4 row_mask:0xf bank_mask:0xf
	v_add_f32_dpp v196, v196, v196 row_ror:4 row_mask:0xf bank_mask:0xf
	v_add_f32_dpp v197, v197, v197 row_ror:4 row_mask:0xf bank_mask:0xf
	v_add_f32_dpp v194, v194, v194 row_ror:2 row_mask:0xf bank_mask:0xf
	v_add_f32_dpp v195, v195, v195 row_ror:2 row_mask:0xf bank_mask:0xf
	v_add_f32_dpp v196, v196, v196 row_ror:2 row_mask:0xf bank_mask:0xf
	v_add_f32_dpp v197, v197, v197 row_ror:2 row_mask:0xf bank_mask:0xf
	v_add_f32_dpp v194, v194, v194 row_ror:1 row_mask:0xf bank_mask:0xf
	v_add_f32_dpp v195, v195, v195 row_ror:1 row_mask:0xf bank_mask:0xf
	v_add_f32_dpp v196, v196, v196 row_ror:1 row_mask:0xf bank_mask:0xf
	v_add_f32_dpp v197, v197, v197 row_ror:1 row_mask:0xf bank_mask:0xf
	s_mov_b64 exec, s[2:3]
	ds_write_b128 v251, v[194:197] offset:512
	s_mov_b64 exec, -1
	global_load_dwordx4 v[32:35], v[200:201], off offset:-4096
	s_waitcnt vmcnt(15)
; template <int L, int N> DEVQ void filt_item(const Params& P, LAS unsigned char* lds, const float* H3v, int d, cf* specd, float* cornerd) {
;     ...
;     for (int k = tid; k < L; k += NTHR) {
;         asm volatile("" ::: "memory");
;         const f32x4* hr = (const f32x4*)(H3v + (size_t)k * 64);
;         f32x4 acc = (f32x4){0.f, 0.f, 0.f, 0.f};
;         f32x4 hv[16];
; #pragma unroll
;         for (int i4 = 0; i4 < 16; ++i4) hv[i4] = hr[i4];
; #pragma unroll
;         for (int i4 = 0; i4 < 16; ++i4) { if ((i4 & 3) == 0) asm volatile("" ::: "memory");
;             acc += hv[i4].x * wc4[4 * i4] + hv[i4].y * wc4[4 * i4 + 1] + hv[i4].z * wc4[4 * i4 + 2] + hv[i4].w * wc4[4 * i4 + 3]; }
	v_mul_f32_e32 v210, v36, v148
	v_mul_f32_e32 v211, v36, v149
	v_mul_f32_e32 v212, v36, v150
	v_mul_f32_e32 v213, v36, v151
	v_fmac_f32_e32 v210, v37, v154
	v_fmac_f32_e32 v211, v37, v155
	v_fmac_f32_e32 v212, v37, v156
	v_fmac_f32_e32 v213, v37, v157
	v_fmac_f32_e32 v210, v38, v158
	v_fmac_f32_e32 v211, v38, v159
	v_fmac_f32_e32 v212, v38, v160
	v_fmac_f32_e32 v213, v38, v161
	v_fmac_f32_e32 v210, v39, v162
	v_fmac_f32_e32 v211, v39, v163
	v_fmac_f32_e32 v212, v39, v164
	v_fmac_f32_e32 v213, v39, v165
	v_add_f32_dpp v210, v210, v210 row_ror:8 row_mask:0xf bank_mask:0xf
	v_add_f32_dpp v211, v211, v211 row_ror:8 row_mask:0xf bank_mask:0xf
	v_add_f32_dpp v212, v212, v212 row_ror:8 row_mask:0xf bank_mask:0xf
	v_add_f32_dpp v213, v213, v213 row_ror:8 row_mask:0xf bank_mask:0xf
	v_add_f32_dpp v210, v210, v210 row_ror:4 row_mask:0xf bank_mask:0xf
	v_add_f32_dpp v211, v211, v211 row_ror:4 row_mask:0xf bank_mask:0xf
	v_add_f32_dpp v212, v212, v212 row_ror:4 row_mask:0xf bank_mask:0xf
	v_add_f32_dpp v213, v213, v213 row_ror:4 row_mask:0xf bank_mask:0xf
	v_add_f32_dpp v210, v210, v210 row_ror:2 row_mask:0xf bank_mask:0xf
	v_add_f32_dpp v211, v211, v211 row_ror:2 row_mask:0xf bank_mask:0xf
	v_add_f32_dpp v212, v212, v212 row_ror:2 row_mask:0xf bank_mask:0xf
	v_add_f32_dpp v213, v213, v213 row_ror:2 row_mask:0xf bank_mask:0xf
	v_add_f32_dpp v210, v210, v210 row_ror:1 row_mask:0xf bank_mask:0xf
	v_add_f32_dpp v211, v211, v211 row_ror:1 row_mask:0xf bank_mask:0xf
	v_add_f32_dpp v212, v212, v212 row_ror:1 row_mask:0xf bank_mask:0xf
	v_add_f32_dpp v213, v213, v213 row_ror:1 row_mask:0xf bank_mask:0xf
	s_mov_b64 exec, s[2:3]
	ds_write_b128 v251, v[210:213] offset:576
	s_mov_b64 exec, -1
	global_load_dwordx4 v[36:39], v[200:201], off offset:-3072
	s_waitcnt vmcnt(15)
	v_mul_f32_e32 v194, v40, v148
	v_mul_f32_e32 v195, v40, v149
	v_mul_f32_e32 v196, v40, v150
	v_mul_f32_e32 v197, v40, v151
	v_fmac_f32_e32 v194, v41, v154
	v_fmac_f32_e32 v195, v41, v155
	v_fmac_f32_e32 v196, v41, v156
	v_fmac_f32_e32 v197, v41, v157
	v_fmac_f32_e32 v194, v42, v158
	v_fmac_f32_e32 v195, v42, v159
	v_fmac_f32_e32 v196, v42, v160
	v_fmac_f32_e32 v197, v42, v161
	v_fmac_f32_e32 v194, v43, v162
	v_fmac_f32_e32 v195, v43, v163
	v_fmac_f32_e32 v196, v43, v164
	v_fmac_f32_e32 v197, v43, v165
	v_add_f32_dpp v194, v194, v194 row_ror:8 row_mask:0xf bank_mask:0xf
	v_add_f32_dpp v195, v195, v195 row_ror:8 row_mask:0xf bank_mask:0xf
	v_add_f32_dpp v196, v196, v196 row_ror:8 row_mask:0xf bank_mask:0xf
	v_add_f32_dpp v197, v197, v197 row_ror:8 row_mask:0xf bank_mask:0xf
	v_add_f32_dpp v194, v194, v194 row_ror:4 row_mask:0xf bank_mask:0xf
	v_add_f32_dpp v195, v195, v195 row_ror:4 row_mask:0xf bank_mask:0xf
	v_add_f32_dpp v196, v196, v196 row_ror:4 row_mask:0xf bank_mask:0xf
	v_add_f32_dpp v197, v197, v197 row_ror:4 row_mask:0xf bank_mask:0xf
	v_add_f32_dpp v194, v194, v194 row_ror:2 row_mask:0xf bank_mask:0xf
	v_add_f32_dpp v195, v195, v195 row_ror:2 row_mask:0xf bank_mask:0xf
	v_add_f32_dpp v196, v196, v196 row_ror:2 row_mask:0xf bank_mask:0xf
	v_add_f32_dpp v197, v197, v197 row_ror:2 row_mask:0xf bank_mask:0xf
	v_add_f32_dpp v194, v194, v194 row_ror:1 row_mask:0xf bank_mask:0xf
	v_add_f32_dpp v195, v195, v195 row_ror:1 row_mask:0xf bank_mask:0xf
	v_add_f32_dpp v196, v196, v196 row_ror:1 row_mask:0xf bank_mask:0xf
	v_add_f32_dpp v197, v197, v197 row_ror:1 row_mask:0xf bank_mask:0xf
	s_mov_b64 exec, s[2:3]
	ds_write_b128 v251, v[194:197] offset:640
	s_mov_b64 exec, -1
	global_load_dwordx4 v[40:43], v[200:201], off offset:-2048
	s_waitcnt vmcnt(15)
	v_mul_f32_e32 v210, v44, v148
	v_mul_f32_e32 v211, v44, v149
	v_mul_f32_e32 v212, v44, v150
	v_mul_f32_e32 v213, v44, v151
	v_fmac_f32_e32 v210, v45, v154
	v_fmac_f32_e32 v211, v45, v155
	v_fmac_f32_e32 v212, v45, v156
	v_fmac_f32_e32 v213, v45, v157
	v_fmac_f32_e32 v210, v46, v158
	v_fmac_f32_e32 v211, v46, v159
	v_fmac_f32_e32 v212, v46, v160
	v_fmac_f32_e32 v213, v46, v161
	v_fmac_f32_e32 v210, v47, v162
	v_fmac_f32_e32 v211, v47, v163
	v_fmac_f32_e32 v212, v47, v164
	v_fmac_f32_e32 v213, v47, v165
	v_add_f32_dpp v210, v210, v210 row_ror:8 row_mask:0xf bank_mask:0xf
	v_add_f32_dpp v211, v211, v211 row_ror:8 row_mask:0xf bank_mask:0xf
	v_add_f32_dpp v212, v212, v212 row_ror:8 row_mask:0xf bank_mask:0xf
	v_add_f32_dpp v213, v213, v213 row_ror:8 row_mask:0xf bank_mask:0xf
	v_add_f32_dpp v210, v210, v210 row_ror:4 row_mask:0xf bank_mask:0xf
	v_add_f32_dpp v211, v211, v211 row_ror:4 row_mask:0xf bank_mask:0xf
	v_add_f32_dpp v212, v212, v212 row_ror:4 row_mask:0xf bank_mask:0xf
	v_add_f32_dpp v213, v213, v213 row_ror:4 row_mask:0xf bank_mask:0xf
	v_add_f32_dpp v210, v210, v210 row_ror:2 row_mask:0xf bank_mask:0xf
	v_add_f32_dpp v211, v211, v211 row_ror:2 row_mask:0xf bank_mask:0xf
	v_add_f32_dpp v212, v212, v212 row_ror:2 row_mask:0xf bank_mask:0xf
	v_add_f32_dpp v213, v213, v213 row_ror:2 row_mask:0xf bank_mask:0xf
	v_add_f32_dpp v210, v210, v210 row_ror:1 row_mask:0xf bank_mask:0xf
	v_add_f32_dpp v211, v211, v211 row_ror:1 row_mask:0xf bank_mask:0xf
	v_add_f32_dpp v212, v212, v212 row_ror:1 row_mask:0xf bank_mask:0xf
	v_add_f32_dpp v213, v213, v213 row_ror:1 row_mask:0xf bank_mask:0xf
	s_mov_b64 exec, s[2:3]
	ds_write_b128 v251, v[210:213] offset:704
	s_mov_b64 exec, -1
	global_load_dwordx4 v[44:47], v[200:201], off offset:-1024
	s_waitcnt vmcnt(15)
; template <int L, int N> DEVQ void filt_item(const Params& P, LAS unsigned char* lds, const float* H3v, int d, cf* specd, float* cornerd) {
;     ...
;     for (int k = tid; k < L; k += NTHR) {
;         asm volatile("" ::: "memory");
;         const f32x4* hr = (const f32x4*)(H3v + (size_t)k * 64);
;         f32x4 acc = (f32x4){0.f, 0.f, 0.f, 0.f};
;         f32x4 hv[16];
; #pragma unroll
;         for (int i4 = 0; i4 < 16; ++i4) hv[i4] = hr[i4];
; #pragma unroll
;         for (int i4 = 0; i4 < 16; ++i4) { if ((i4 & 3) == 0) asm volatile("" ::: "memory");
;             acc += hv[i4].x * wc4[4 * i4] + hv[i4].y * wc4[4 * i4 + 1] + hv[i4].z * wc4[4 * i4 + 2] + hv[i4].w * wc4[4 * i4 + 3]; }
	v_mul_f32_e32 v194, v48, v148
	v_mul_f32_e32 v195, v48, v149
	v_mul_f32_e32 v196, v48, v150
	v_mul_f32_e32 v197, v48, v151
	v_fmac_f32_e32 v194, v49, v154
	v_fmac_f32_e32 v195, v49, v155
	v_fmac_f32_e32 v196, v49, v156
	v_fmac_f32_e32 v197, v49, v157
	v_fmac_f32_e32 v194, v50, v158
	v_fmac_f32_e32 v195, v50, v159
	v_fmac_f32_e32 v196, v50, v160
	v_fmac_f32_e32 v197, v50, v161
	v_fmac_f32_e32 v194, v51, v162
	v_fmac_f32_e32 v195, v51, v163
	v_fmac_f32_e32 v196, v51, v164
	v_fmac_f32_e32 v197, v51, v165
	v_add_f32_dpp v194, v194, v194 row_ror:8 row_mask:0xf bank_mask:0xf
	v_add_f32_dpp v195, v195, v195 row_ror:8 row_mask:0xf bank_mask:0xf
	v_add_f32_dpp v196, v196, v196 row_ror:8 row_mask:0xf bank_mask:0xf
	v_add_f32_dpp v197, v197, v197 row_ror:8 row_mask:0xf bank_mask:0xf
	v_add_f32_dpp v194, v194, v194 row_ror:4 row_mask:0xf bank_mask:0xf
	v_add_f32_dpp v195, v195, v195 row_ror:4 row_mask:0xf bank_mask:0xf
	v_add_f32_dpp v196, v196, v196 row_ror:4 row_mask:0xf bank_mask:0xf
	v_add_f32_dpp v197, v197, v197 row_ror:4 row_mask:0xf bank_mask:0xf
	v_add_f32_dpp v194, v194, v194 row_ror:2 row_mask:0xf bank_mask:0xf
	v_add_f32_dpp v195, v195, v195 row_ror:2 row_mask:0xf bank_mask:0xf
	v_add_f32_dpp v196, v196, v196 row_ror:2 row_mask:0xf bank_mask:0xf
	v_add_f32_dpp v197, v197, v197 row_ror:2 row_mask:0xf bank_mask:0xf
	v_add_f32_dpp v194, v194, v194 row_ror:1 row_mask:0xf bank_mask:0xf
	v_add_f32_dpp v195, v195, v195 row_ror:1 row_mask:0xf bank_mask:0xf
	v_add_f32_dpp v196, v196, v196 row_ror:1 row_mask:0xf bank_mask:0xf
	v_add_f32_dpp v197, v197, v197 row_ror:1 row_mask:0xf bank_mask:0xf
	s_mov_b64 exec, s[2:3]
	ds_write_b128 v251, v[194:197] offset:768
	s_mov_b64 exec, -1
	global_load_dwordx4 v[48:51], v[200:201], off offset:0
	s_waitcnt vmcnt(15)
	v_mul_f32_e32 v210, v52, v148
	v_mul_f32_e32 v211, v52, v149
	v_mul_f32_e32 v212, v52, v150
	v_mul_f32_e32 v213, v52, v151
	v_fmac_f32_e32 v210, v53, v154
	v_fmac_f32_e32 v211, v53, v155
	v_fmac_f32_e32 v212, v53, v156
	v_fmac_f32_e32 v213, v53, v157
	v_fmac_f32_e32 v210, v54, v158
	v_fmac_f32_e32 v211, v54, v159
	v_fmac_f32_e32 v212, v54, v160
	v_fmac_f32_e32 v213, v54, v161
	v_fmac_f32_e32 v210, v55, v162
	v_fmac_f32_e32 v211, v55, v163
	v_fmac_f32_e32 v212, v55, v164
	v_fmac_f32_e32 v213, v55, v165
	v_add_f32_dpp v210, v210, v210 row_ror:8 row_mask:0xf bank_mask:0xf
	v_add_f32_dpp v211, v211, v211 row_ror:8 row_mask:0xf bank_mask:0xf
	v_add_f32_dpp v212, v212, v212 row_ror:8 row_mask:0xf bank_mask:0xf
	v_add_f32_dpp v213, v213, v213 row_ror:8 row_mask:0xf bank_mask:0xf
	v_add_f32_dpp v210, v210, v210 row_ror:4 row_mask:0xf bank_mask:0xf
	v_add_f32_dpp v211, v211, v211 row_ror:4 row_mask:0xf bank_mask:0xf
	v_add_f32_dpp v212, v212, v212 row_ror:4 row_mask:0xf bank_mask:0xf
	v_add_f32_dpp v213, v213, v213 row_ror:4 row_mask:0xf bank_mask:0xf
	v_add_f32_dpp v210, v210, v210 row_ror:2 row_mask:0xf bank_mask:0xf
	v_add_f32_dpp v211, v211, v211 row_ror:2 row_mask:0xf bank_mask:0xf
	v_add_f32_dpp v212, v212, v212 row_ror:2 row_mask:0xf bank_mask:0xf
	v_add_f32_dpp v213, v213, v213 row_ror:2 row_mask:0xf bank_mask:0xf
	v_add_f32_dpp v210, v210, v210 row_ror:1 row_mask:0xf bank_mask:0xf
	v_add_f32_dpp v211, v211, v211 row_ror:1 row_mask:0xf bank_mask:0xf
	v_add_f32_dpp v212, v212, v212 row_ror:1 row_mask:0xf bank_mask:0xf
	v_add_f32_dpp v213, v213, v213 row_ror:1 row_mask:0xf bank_mask:0xf
	s_mov_b64 exec, s[2:3]
	ds_write_b128 v251, v[210:213] offset:832
	s_mov_b64 exec, -1
	global_load_dwordx4 v[52:55], v[200:201], off offset:1024
	s_waitcnt vmcnt(15)
; template <int L, int N> DEVQ void filt_item(const Params& P, LAS unsigned char* lds, const float* H3v, int d, cf* specd, float* cornerd) {
;     ...
;     for (int k = tid; k < L; k += NTHR) {
;         asm volatile("" ::: "memory");
;         const f32x4* hr = (const f32x4*)(H3v + (size_t)k * 64);
;         f32x4 acc = (f32x4){0.f, 0.f, 0.f, 0.f};
;         f32x4 hv[16];
; #pragma unroll
;         for (int i4 = 0; i4 < 16; ++i4) hv[i4] = hr[i4];
; #pragma unroll
;         for (int i4 = 0; i4 < 16; ++i4) { if ((i4 & 3) == 0) asm volatile("" ::: "memory");
;             acc += hv[i4].x * wc4[4 * i4] + hv[i4].y * wc4[4 * i4 + 1] + hv[i4].z * wc4[4 * i4 + 2] + hv[i4].w * wc4[4 * i4 + 3]; }
;         const float dec = expf(-((float)k / (float)(L - 1)) * delta);
;         acc *= dec;
;         if (k <= N / 2) X[swz(k)] = cf{acc.x * invN, acc.z * invN};
	v_mul_f32_e32 v194, v56, v148
	v_mul_f32_e32 v195, v56, v149
	v_mul_f32_e32 v196, v56, v150
	v_mul_f32_e32 v197, v56, v151
	v_fmac_f32_e32 v194, v57, v154
	v_fmac_f32_e32 v195, v57, v155
	v_fmac_f32_e32 v196, v57, v156
	v_fmac_f32_e32 v197, v57, v157
	v_fmac_f32_e32 v194, v58, v158
	v_fmac_f32_e32 v195, v58, v159
	v_fmac_f32_e32 v196, v58, v160
	v_fmac_f32_e32 v197, v58, v161
	v_fmac_f32_e32 v194, v59, v162
	v_fmac_f32_e32 v195, v59, v163
	v_fmac_f32_e32 v196, v59, v164
	v_fmac_f32_e32 v197, v59, v165
	v_add_f32_dpp v194, v194, v194 row_ror:8 row_mask:0xf bank_mask:0xf
	v_add_f32_dpp v195, v195, v195 row_ror:8 row_mask:0xf bank_mask:0xf
	v_add_f32_dpp v196, v196, v196 row_ror:8 row_mask:0xf bank_mask:0xf
	v_add_f32_dpp v197, v197, v197 row_ror:8 row_mask:0xf bank_mask:0xf
	v_add_f32_dpp v194, v194, v194 row_ror:4 row_mask:0xf bank_mask:0xf
	v_add_f32_dpp v195, v195, v195 row_ror:4 row_mask:0xf bank_mask:0xf
	v_add_f32_dpp v196, v196, v196 row_ror:4 row_mask:0xf bank_mask:0xf
	v_add_f32_dpp v197, v197, v197 row_ror:4 row_mask:0xf bank_mask:0xf
	v_add_f32_dpp v194, v194, v194 row_ror:2 row_mask:0xf bank_mask:0xf
	v_add_f32_dpp v195, v195, v195 row_ror:2 row_mask:0xf bank_mask:0xf
	v_add_f32_dpp v196, v196, v196 row_ror:2 row_mask:0xf bank_mask:0xf
	v_add_f32_dpp v197, v197, v197 row_ror:2 row_mask:0xf bank_mask:0xf
	v_add_f32_dpp v194, v194, v194 row_ror:1 row_mask:0xf bank_mask:0xf
	v_add_f32_dpp v195, v195, v195 row_ror:1 row_mask:0xf bank_mask:0xf
	v_add_f32_dpp v196, v196, v196 row_ror:1 row_mask:0xf bank_mask:0xf
	v_add_f32_dpp v197, v197, v197 row_ror:1 row_mask:0xf bank_mask:0xf
	s_mov_b64 exec, s[2:3]
	ds_write_b128 v251, v[194:197] offset:896
	s_mov_b64 exec, -1
	global_load_dwordx4 v[56:59], v[200:201], off offset:2048
	s_waitcnt vmcnt(15)
	v_mul_f32_e32 v210, v60, v148
	v_mul_f32_e32 v211, v60, v149
	v_mul_f32_e32 v212, v60, v150
	v_mul_f32_e32 v213, v60, v151
	v_fmac_f32_e32 v210, v61, v154
	v_fmac_f32_e32 v211, v61, v155
	v_fmac_f32_e32 v212, v61, v156
	v_fmac_f32_e32 v213, v61, v157
	v_fmac_f32_e32 v210, v62, v158
	v_fmac_f32_e32 v211, v62, v159
	v_fmac_f32_e32 v212, v62, v160
	v_fmac_f32_e32 v213, v62, v161
	v_fmac_f32_e32 v210, v63, v162
	v_fmac_f32_e32 v211, v63, v163
	v_fmac_f32_e32 v212, v63, v164
	v_fmac_f32_e32 v213, v63, v165
	v_add_f32_dpp v210, v210, v210 row_ror:8 row_mask:0xf bank_mask:0xf
	v_add_f32_dpp v211, v211, v211 row_ror:8 row_mask:0xf bank_mask:0xf
	v_add_f32_dpp v212, v212, v212 row_ror:8 row_mask:0xf bank_mask:0xf
	v_add_f32_dpp v213, v213, v213 row_ror:8 row_mask:0xf bank_mask:0xf
	v_add_f32_dpp v210, v210, v210 row_ror:4 row_mask:0xf bank_mask:0xf
	v_add_f32_dpp v211, v211, v211 row_ror:4 row_mask:0xf bank_mask:0xf
	v_add_f32_dpp v212, v212, v212 row_ror:4 row_mask:0xf bank_mask:0xf
	v_add_f32_dpp v213, v213, v213 row_ror:4 row_mask:0xf bank_mask:0xf
	v_add_f32_dpp v210, v210, v210 row_ror:2 row_mask:0xf bank_mask:0xf
	v_add_f32_dpp v211, v211, v211 row_ror:2 row_mask:0xf bank_mask:0xf
	v_add_f32_dpp v212, v212, v212 row_ror:2 row_mask:0xf bank_mask:0xf
	v_add_f32_dpp v213, v213, v213 row_ror:2 row_mask:0xf bank_mask:0xf
	v_add_f32_dpp v210, v210, v210 row_ror:1 row_mask:0xf bank_mask:0xf
	v_add_f32_dpp v211, v211, v211 row_ror:1 row_mask:0xf bank_mask:0xf
	v_add_f32_dpp v212, v212, v212 row_ror:1 row_mask:0xf bank_mask:0xf
	v_add_f32_dpp v213, v213, v213 row_ror:1 row_mask:0xf bank_mask:0xf
	s_mov_b64 exec, s[2:3]
	ds_write_b128 v251, v[210:213] offset:960
	s_mov_b64 exec, -1
	global_load_dwordx4 v[60:63], v[200:201], off offset:3072
	s_waitcnt lgkmcnt(0)
	ds_read_b128 v[0:3], v250
	v_cvt_f32_i32_e32 v4, v75
	s_waitcnt lgkmcnt(0)
	s_mov_b64 exec, s[20:21]
	v_div_scale_f32 v5, s[2:3], s23, s23, v4
	v_rcp_f32_e32 v6, v5
	s_mov_b32 s2, 0xc2ce8ed0
	v_fma_f32 v7, -v5, v6, 1.0
	v_fmac_f32_e32 v6, v7, v6
	v_div_scale_f32 v7, vcc, v4, s23, v4
	v_mul_f32_e32 v8, v7, v6
	v_fma_f32 v9, -v5, v8, v7
	v_fmac_f32_e32 v8, v9, v6
	v_fma_f32 v5, -v5, v8, v7
	v_div_fmas_f32 v5, v5, v6, v8
	v_div_fixup_f32 v4, v5, s23, v4
	v_mul_f32_e64 v4, |v74|, v4
	v_mul_f32_e32 v5, 0x3fb8aa3b, v4
	v_fma_f32 v6, v4, s18, -v5
	v_rndne_f32_e32 v7, v5
	v_fmac_f32_e32 v6, 0x32a5705f, v4
	v_sub_f32_e32 v5, v5, v7
	v_add_f32_e32 v5, v5, v6
	v_exp_f32_e32 v5, v5
	v_cvt_i32_f32_e32 v6, v7
	v_cmp_ngt_f32_e32 vcc, s2, v4
	s_mov_b32 s2, 0x42b17218
	v_ldexp_f32 v5, v5, v6
	v_cndmask_b32_e32 v5, 0, v5, vcc
	v_cmp_nlt_f32_e32 vcc, s2, v4
	s_movk_i32 s2, 0x2001
	s_nop 0
	v_cndmask_b32_e32 v4, v188, v5, vcc
	v_pk_mul_f32 v[0:1], v[4:5], v[0:1] op_sel_hi:[0,1]
	v_pk_mul_f32 v[2:3], v[4:5], v[2:3] op_sel_hi:[0,1]
	v_cmp_gt_i32_e32 vcc, s2, v75
	s_and_saveexec_b64 s[20:21], vcc
	s_cbranch_execz .LBB0_629
	v_ashrrev_i32_e32 v6, 5, v75
	v_lshlrev_b32_e32 v7, 2, v6
	v_and_b32_e32 v7, 28, v7
	v_and_b32_e32 v6, 3, v6
	v_mov_b32_e32 v4, v0
	v_mov_b32_e32 v5, v2
	s_mov_b32 s2, 0x38800000
	v_bitop3_b32 v6, v7, v75, v6 bitop3:0x36
	v_pk_mul_f32 v[4:5], v[4:5], s[2:3] op_sel_hi:[1,0]
	v_lshl_add_u32 v6, v6, 3, 0
	ds_write_b64 v6, v[4:5]

; #define LAS __attribute__((address_space(3)))
; template <int L, int N> DEVQ void filt_item(const Params& P, LAS unsigned char* lds, const float* H3v, int d, cf* specd, float* cornerd) {
;     ...
;     __syncthreads();
;     if (tid < 64) { const int o = tid >> 5, kk = tid & 31; float v = 0.f;
;         const LAS float* hf = edge + 64 * o; const LAS float* hb = hf + 32;
;         if (kk < 15) v = hf[16 + kk] - hb[14 - kk];
;         else if (kk >= 16) { const int q = kk - 16; v = hb[15 + q] - hf[15 - q]; }
;         cornerd[tid] = v; }
.LBB0_633:
	s_waitcnt vmcnt(0)
	s_or_b64 exec, exec, s[0:1]
	s_waitcnt lgkmcnt(0)
	s_barrier
	s_and_saveexec_b64 s[0:1], s[4:5]
	s_cbranch_execz .LBB0_641
	s_waitcnt vmcnt(0)
	v_lshlrev_b32_e32 v0, 3, v64
	v_and_b32_e32 v1, 31, v64
	v_and_b32_e32 v0, 0xffffff00, v0
	v_readlane_b32 s2, v254, 31
	v_cmp_lt_u32_e32 vcc, 14, v1
	s_nop 0
	v_add_u32_e32 v2, s2, v0
	s_and_saveexec_b64 s[2:3], vcc
	s_xor_b64 s[4:5], exec, s[2:3]
	s_cbranch_execz .LBB0_638
	v_cmp_ne_u32_e32 vcc, 15, v1
	v_mov_b32_e32 v0, 0
	s_and_saveexec_b64 s[14:15], vcc
	s_cbranch_execz .LBB0_637
	v_lshl_add_u32 v0, v1, 2, v2
	v_xor_b32_e32 v1, 31, v1
	v_lshl_add_u32 v1, v1, 2, v2
	ds_read_b32 v0, v0 offset:124
	ds_read_b32 v1, v1
	s_waitcnt lgkmcnt(0)
	v_sub_f32_e32 v0, v0, v1
